# K-blocked layouts for weights and norm outputs (contiguous 1KB LDS-DMA), softmax max-subtraction folded into MFMA accumulator init
# speedup vs baseline: 1.1863x; 1.0874x over previous
; DI void transpose_loop(const Params& p, int n_items, char* smem) {
;     ...
;     TR_PUT(v0, 0) TR_PUT(v1, 1) TR_PUT(v2, 2) TR_PUT(v3, 3)
;     __syncthreads();
; #pragma unroll
;     for (int i = 0; i < 2; ++i) {
;       int id = tid + 256 * i, n = id >> 3, k8 = id & 7;
;       const unsigned* sp = (const unsigned*)(sT + n * 66 + k8 * 8);
;       uint4 w; w.x = sp[0]; w.y = sp[1]; w.z = sp[2]; w.w = sp[3];
;       int j = cur.n0 + n, drow = j;
;       if (cur.mode != 0) drow = 128 * (j >> 6) + 64 * ((j >> 5) & 1) + (j & 31) + (cur.mode == 2 ? 32 : 0);
;       *(uint4*)(cur.dst + (size_t)drow * cur.K + cur.k0 + k8 * 8) = w;
;     }
.LBB0_50:
	s_waitcnt vmcnt(0)
	v_cvt_pk_bf16_f32 v0, v0, s0
	s_cmp_eq_u32 s43, 0
	ds_write_b16 v36, v0 offset:96
	v_cvt_pk_bf16_f32 v0, v1, s0
	s_cselect_b64 vcc, -1, 0
	s_ashr_i32 s17, s16, 31
	ds_write_b16 v36, v0 offset:228
	v_cvt_pk_bf16_f32 v0, v2, s0
	s_lshl_b64 s[16:17], s[16:17], 1
	ds_write_b16 v36, v0 offset:360
	v_cvt_pk_bf16_f32 v0, v3, s0
	s_add_u32 s14, s14, s16
	ds_write_b16 v36, v0 offset:492
	v_add_u32_e32 v0, s44, v37
	s_addc_u32 s15, s15, s17
	v_cvt_pk_bf16_f32 v8, v8, s0
	v_cvt_pk_bf16_f32 v4, v4, s0
	s_cmp_eq_u32 s43, 2
	v_lshlrev_b32_e32 v1, 1, v0
	ds_write_b16 v36, v8 offset:32
	v_cvt_pk_bf16_f32 v8, v9, s0
	ds_write_b16 v36, v4 offset:64
	v_cvt_pk_bf16_f32 v4, v5, s0
	s_cselect_b32 s12, 32, 0
	v_and_b32_e32 v1, 0xffffffc0, v1
	v_and_b32_e32 v2, 31, v0
	v_cvt_pk_bf16_f32 v12, v12, s0
	ds_write_b16 v36, v8 offset:164
	v_cvt_pk_bf16_f32 v8, v10, s0
	ds_write_b16 v36, v4 offset:196
	v_cvt_pk_bf16_f32 v4, v6, s0
	v_or3_b32 v1, v2, v1, s12
	ds_write_b16 v36, v12
	v_cvt_pk_bf16_f32 v12, v13, s0
	ds_write_b16 v36, v8 offset:296
	v_cvt_pk_bf16_f32 v8, v11, s0
	ds_write_b16 v36, v4 offset:328
	v_cvt_pk_bf16_f32 v4, v7, s0
	v_cndmask_b32_e32 v0, v1, v0, vcc
	ds_write_b16 v36, v12 offset:132
	v_cvt_pk_bf16_f32 v12, v14, s0
	ds_write_b16 v36, v8 offset:428
	ds_write_b16 v36, v4 offset:460
	v_lshl_add_u64 v[8:9], s[14:15], 0, v[32:33]
	v_mad_u64_u32 v[4:5], s[14:15], v0, s42, 0
	ds_write_b16 v36, v12 offset:264
	v_cvt_pk_bf16_f32 v12, v15, s0
	v_ashrrev_i32_e32 v1, 31, v0
	v_mov_b32_e32 v0, v5
	ds_write_b16 v36, v12 offset:396
	s_waitcnt lgkmcnt(0)
	s_barrier
	v_mad_u64_u32 v[6:7], s[14:15], v1, s42, v[0:1]
	ds_read2_b32 v[0:1], v39 offset1:1
	ds_read2_b32 v[2:3], v39 offset0:2 offset1:3
	v_mov_b32_e32 v5, v6
	v_lshl_add_u64 v[10:11], v[4:5], 1, v[8:9]
	ds_read2_b32 v[4:5], v40 offset1:1
	ds_read2_b32 v[6:7], v40 offset0:2 offset1:3
	s_mov_b32 s43, s47
	s_waitcnt lgkmcnt(2)
	v_subrev_u32_e32 v240, s24, v10
	v_add_u32_e32 v240, 0xe5a80000, v240
	v_add_u32_e32 v241, 0xfe940000, v240
	v_mov_b32_e32 v244, 0x16c0000
	v_cmp_le_u32_e64 s[100:101], v244, v240
	v_mov_b32_e32 v242, 0
	v_mov_b32_e32 v243, 1920
	v_cndmask_b32_e64 v240, v240, v241, s[100:101]
	v_mov_b32_e32 v244, 0x3c0000
	v_cmp_le_u32_e64 s[100:101], v244, v240
	v_mov_b32_e32 v245, 1024
	s_nop 0
	v_cndmask_b32_e64 v242, v242, v244, s[100:101]
	v_cndmask_b32_e64 v243, v243, v245, s[100:101]
	v_mov_b32_e32 v244, 0x5c0000
	v_cmp_le_u32_e64 s[100:101], v244, v240
	v_mov_b32_e32 v245, 5632
	s_nop 0
	v_cndmask_b32_e64 v242, v242, v244, s[100:101]
	v_cndmask_b32_e64 v243, v243, v245, s[100:101]
	v_mov_b32_e32 v244, 0x10c0000
	v_cmp_le_u32_e64 s[100:101], v244, v240
	v_mov_b32_e32 v245, 1024
	s_nop 0
	v_cndmask_b32_e64 v242, v242, v244, s[100:101]
	v_cndmask_b32_e64 v243, v243, v245, s[100:101]
	v_sub_u32_e32 v246, v240, v242
	v_lshrrev_b32_e32 v247, 11, v246
	v_and_b32_e32 v248, 0x7ff, v246
	v_lshrrev_b32_e32 v244, 9, v246
	v_mul_u32_u24_e32 v244, 0x1746, v244
	v_lshrrev_b32_e32 v244, 16, v244
	v_mul_u32_u24_e32 v245, 0x1600, v244
	v_sub_u32_e32 v245, v246, v245
	v_cndmask_b32_e64 v247, v247, v244, s[100:101]
	v_cndmask_b32_e64 v248, v248, v245, s[100:101]
	v_lshrrev_b32_e32 v244, 6, v248
	v_mul_u32_u24_e32 v244, v244, v243
	v_add_u32_e32 v244, v244, v247
	v_and_b32_e32 v248, 63, v248
	v_lshl_add_u32 v244, v244, 6, v248
	v_sub_u32_e32 v249, v244, v246
	v_mov_b32_e32 v244, 0x1640000
	v_cmp_le_u32_e64 s[100:101], v244, v240
	s_nop 1
	v_cndmask_b32_e64 v249, v249, 0, s[100:101]
	v_ashrrev_i32_e32 v244, 31, v249
	v_add_co_u32_e64 v238, s[100:101], v10, v249
	s_nop 1
	v_addc_co_u32_e64 v239, s[100:101], v11, v244, s[100:101]
	global_store_dwordx4 v[238:239], v[0:3], off
	s_mov_b32 s16, s37
	v_mov_b32_e32 v10, v22
	v_add_u32_e32 v0, s44, v38
	v_lshlrev_b32_e32 v1, 1, v0
	v_and_b32_e32 v1, 0xffffffc0, v1
	v_and_b32_e32 v2, 31, v0
	v_or3_b32 v1, v2, v1, s12
	v_cndmask_b32_e32 v0, v1, v0, vcc
	v_ashrrev_i32_e32 v3, 31, v0
	v_mad_u64_u32 v[0:1], s[14:15], v0, s42, 0
	v_mov_b32_e32 v2, v1
	v_mad_u64_u32 v[2:3], s[14:15], v3, s42, v[2:3]
	v_mov_b32_e32 v1, v2
	v_lshl_add_u64 v[0:1], v[0:1], 1, v[8:9]
	s_waitcnt lgkmcnt(0)
	v_subrev_u32_e32 v240, s24, v0
	v_add_u32_e32 v240, 0xe5a80000, v240
	v_add_u32_e32 v241, 0xfe940000, v240
	v_mov_b32_e32 v244, 0x16c0000
	v_cmp_le_u32_e64 s[100:101], v244, v240
	v_mov_b32_e32 v242, 0
	v_mov_b32_e32 v243, 1920
	v_cndmask_b32_e64 v240, v240, v241, s[100:101]
	v_mov_b32_e32 v244, 0x3c0000
	v_cmp_le_u32_e64 s[100:101], v244, v240
	v_mov_b32_e32 v245, 1024
	s_nop 0
	v_cndmask_b32_e64 v242, v242, v244, s[100:101]
	v_cndmask_b32_e64 v243, v243, v245, s[100:101]
	v_mov_b32_e32 v244, 0x5c0000
	v_cmp_le_u32_e64 s[100:101], v244, v240
	v_mov_b32_e32 v245, 5632
	s_nop 0
	v_cndmask_b32_e64 v242, v242, v244, s[100:101]
	v_cndmask_b32_e64 v243, v243, v245, s[100:101]
	v_mov_b32_e32 v244, 0x10c0000
	v_cmp_le_u32_e64 s[100:101], v244, v240
	v_mov_b32_e32 v245, 1024
	s_nop 0
	v_cndmask_b32_e64 v242, v242, v244, s[100:101]
	v_cndmask_b32_e64 v243, v243, v245, s[100:101]
	v_sub_u32_e32 v246, v240, v242
	v_lshrrev_b32_e32 v247, 11, v246
	v_and_b32_e32 v248, 0x7ff, v246
	v_lshrrev_b32_e32 v244, 9, v246
	v_mul_u32_u24_e32 v244, 0x1746, v244
	v_lshrrev_b32_e32 v244, 16, v244
	v_mul_u32_u24_e32 v245, 0x1600, v244
	v_sub_u32_e32 v245, v246, v245
	v_cndmask_b32_e64 v247, v247, v244, s[100:101]
	v_cndmask_b32_e64 v248, v248, v245, s[100:101]
	v_lshrrev_b32_e32 v244, 6, v248
	v_mul_u32_u24_e32 v244, v244, v243
	v_add_u32_e32 v244, v244, v247
	v_and_b32_e32 v248, 63, v248
	v_lshl_add_u32 v244, v244, 6, v248
	v_sub_u32_e32 v249, v244, v246
	v_mov_b32_e32 v244, 0x1640000
	v_cmp_le_u32_e64 s[100:101], v244, v240
	s_nop 1
	v_cndmask_b32_e64 v249, v249, 0, s[100:101]
	v_ashrrev_i32_e32 v244, 31, v249
	v_add_co_u32_e64 v238, s[100:101], v0, v249
	s_nop 1
	v_addc_co_u32_e64 v239, s[100:101], v1, v244, s[100:101]
	global_store_dwordx4 v[238:239], v[4:7], off
	s_andn2_b64 vcc, exec, s[18:19]
	s_mov_b64 s[14:15], s[30:31]
	s_mov_b32 s42, s46
	s_mov_b32 s44, s36
	v_mov_b32_e32 v0, v28
	v_mov_b32_e32 v1, v29
	v_mov_b32_e32 v2, v30
	v_mov_b32_e32 v3, v31
	v_mov_b32_e32 v4, v24
	v_mov_b32_e32 v5, v25
	v_mov_b32_e32 v6, v26
	v_mov_b32_e32 v7, v27
	v_mov_b32_e32 v8, v20
	v_mov_b32_e32 v9, v21
	v_mov_b32_e32 v11, v23
	v_mov_b32_e32 v12, v16
	v_mov_b32_e32 v13, v17
	v_mov_b32_e32 v14, v18
	v_mov_b32_e32 v15, v19
	s_barrier
	s_cbranch_vccz .LBB0_78

; DI int get_tid() { int t = threadIdx.x; asm volatile("" : "+v"(t)); return t; }
; DI void phase_norm(const Params& p, int layer, int which  , int nrows) {
;   const int lane = get_tid() & 63, gw = blockIdx.x * 4 + (get_tid() >> 6), nw = gridDim.x * 4;
;   const float* g = (which == 0 ? p.norm1_g : p.norm2_g) + layer * D;
;   const float* mod = (const float*)(p.ws + OFF_MOD) + (size_t)layer * 9 * 6144;
;   bf16_t* H = (bf16_t*)(p.ws + OFF_H);
;   const bool first = (which == 0) && layer == 0;
;   for (int pr = gw; pr < (nrows >> 1); pr += nw) {
;     const int row = pr * 2;
;     const float* xr0 = xold_ptr(p, layer, first, row);
;     const float* xr1 = xold_ptr(p, layer, first, row + 1);
;     const int b9 = row < NLAT ? (row >> 12) : 8;
;     float4 v[2][4];
;     float ss0 = 0.f, ss1 = 0.f;
; #pragma unroll
;     for (int i = 0; i < 4; ++i) {
;       typedef float f4ld __attribute__((ext_vector_type(4)));
;       const f4ld a_ = __builtin_nontemporal_load((const f4ld*)xr0 + lane + 64 * i), b_ = __builtin_nontemporal_load((const f4ld*)xr1 + lane + 64 * i);
;       v[0][i] = make_float4(a_[0], a_[1], a_[2], a_[3]); v[1][i] = make_float4(b_[0], b_[1], b_[2], b_[3]);
;     }
;     const float* sh = mod + b9 * 6144 + (which == 0 ? 0 : 3) * 1024;
;     const float* sc = sh + 1024;
;     float4 gg[4], s4[4], h4[4];
; #pragma unroll
;     for (int i = 0; i < 4; ++i) {
;       const int col = 4 * (lane + 64 * i);
;       gg[i] = *(const float4*)(g + col); s4[i] = *(const float4*)(sc + col); h4[i] = *(const float4*)(sh + col);
;     }
; #pragma unroll
;     for (int i = 0; i < 4; ++i) {
;       ss0 += v[0][i].x * v[0][i].x + v[0][i].y * v[0][i].y + v[0][i].z * v[0][i].z + v[0][i].w * v[0][i].w;
;       ss1 += v[1][i].x * v[1][i].x + v[1][i].y * v[1][i].y + v[1][i].z * v[1][i].z + v[1][i].w * v[1][i].w;
;     }
;     ss0 = wave_sum(ss0); ss1 = wave_sum(ss1);
.LBB0_331:
	v_and_b32_e32 v168, 63, v143
	v_lshlrev_b32_e32 v169, 3, v168
	v_add_u32_e32 v162, s24, v169
	v_add_u32_e32 v162, 0x15980000, v162
	v_lshrrev_b32_e32 v170, 3, v168
	v_mul_u32_u24_e32 v170, 0x220000, v170
	v_and_b32_e32 v171, 7, v168
	v_lshl_add_u32 v170, v171, 3, v170
	v_mov_b32_e32 v171, 0
	v_mov_b32_e32 v160, s24
	v_mov_b32_e32 v161, s25
	v_mov_b32_e32 v172, 0x15980000
	v_mov_b32_e32 v173, 0
	v_lshl_add_u64 v[160:161], v[160:161], 0, v[172:173]
	v_lshl_add_u64 v[160:161], v[160:161], 0, v[170:171]
	v_mov_b32_e32 v164, 0x1100000
	v_mov_b32_e32 v165, 0
	v_mov_b32_e32 v167, 0
	v_mov_b32_e32 v175, 0
	v_mov_b32_e32 v1, v143
	v_mov_b32_e32 v0, v143
	s_movk_i32 s0, 0x4400
	v_ashrrev_i32_e32 v0, 6, v0
	v_add_u32_e32 v55, s34, v0
	v_cmp_gt_i32_e32 vcc, s0, v55
	s_mul_i32 s0, s10, 0xd800
	s_mov_b32 s93, 0x8000
	s_mov_b32 s31, s34
	s_mov_b32 s34, s10
	v_writelane_b32 v234, s0, 46
	s_nop 1
	v_writelane_b32 v234, s1, 47
	s_and_saveexec_b64 s[10:11], vcc
	s_movk_i32 s94, 0x4000
	s_movk_i32 s95, 0x43ff
	s_mov_b32 s52, 0x3a800000
	s_mov_b64 s[80:81], 0x1000
	s_cbranch_execz .LBB0_334
	s_lshl_b32 s0, s34, 10
	s_mov_b32 s1, s92
	s_mov_b32 s13, s51
	v_readlane_b32 s36, v236, 21
	s_mul_i32 s28, s34, 0xd800
	s_lshl_b64 s[0:1], s[0:1], 2
	v_readlane_b32 s48, v236, 33
	v_readlane_b32 s51, v236, 36
	s_mov_b32 s12, s28
	v_cmp_lt_i32_e32 vcc, v202, v196
	v_readlane_b32 s49, v236, 34
	s_mov_b32 s51, s13
	s_add_u32 s0, s48, s0
	s_mov_b32 s29, s92
	v_writelane_b32 v234, s12, 46
	v_and_b32_e32 v2, 63, v1
	v_cndmask_b32_e32 v1, v195, v202, vcc
	v_cmp_lt_i32_e32 vcc, v201, v196
	s_addc_u32 s1, s49, s1
	v_writelane_b32 v234, s13, 47
	s_lshl_b64 s[12:13], s[28:29], 2
	v_readlane_b32 s28, v236, 38
	v_lshlrev_b32_e32 v59, 2, v1
	v_cndmask_b32_e32 v1, v195, v201, vcc
	v_cmp_lt_i32_e32 vcc, v200, v196
	v_lshlrev_b32_e32 v6, 4, v2
	v_mov_b32_e32 v7, v141
	v_readlane_b32 s29, v236, 39
	s_add_u32 s12, s28, s12
	s_waitcnt vmcnt(0)
	v_lshlrev_b32_e32 v66, 2, v1
	v_cndmask_b32_e32 v1, v195, v200, vcc
	v_cmp_lt_i32_e32 vcc, v199, v196
	v_lshl_add_u64 v[32:33], s[0:1], 0, v[6:7]
	v_readlane_b32 s0, v234, 23
	s_addc_u32 s13, s29, s13
	v_lshlrev_b32_e32 v67, 2, v1
	v_cndmask_b32_e32 v1, v195, v199, vcc
	v_cmp_lt_i32_e32 vcc, v198, v196
	v_readlane_b32 s1, v234, 24
	v_readlane_b32 s37, v236, 22
	v_readlane_b32 s40, v236, 25
	v_readlane_b32 s41, v236, 26
	v_lshlrev_b32_e32 v4, 2, v2
	v_lshlrev_b32_e32 v68, 2, v1
	v_cndmask_b32_e32 v1, v195, v198, vcc
	v_cmp_lt_i32_e32 vcc, v197, v196
	s_and_b64 s[0:1], s[0:1], exec
	v_lshlrev_b32_e32 v69, 2, v1
	v_cndmask_b32_e32 v1, v195, v197, vcc
	v_or_b32_e32 v6, 0x100, v4
	v_or_b32_e32 v8, 0x200, v4
	v_or_b32_e32 v10, 0x300, v4
	s_cselect_b32 s0, s14, s41
	s_cselect_b32 s1, s35, s40
	s_cselect_b32 s28, s23, s37
	s_cselect_b32 s29, s22, s36
	v_lshlrev_b32_e32 v12, 3, v2
	v_mov_b32_e32 v13, v141
	v_readlane_b32 s36, v234, 14
	v_lshlrev_b32_e32 v70, 2, v1
	v_lshl_add_u64 v[34:35], s[74:75], 0, v[12:13]
	v_lshl_add_u32 v36, v0, 1, s36
	s_mov_b64 s[36:37], 0
	v_mov_b32_e32 v71, s0
	v_mov_b32_e32 v72, s28
	v_mov_b32_e32 v73, s1
	v_mov_b32_e32 v74, s29
	v_lshlrev_b32_e32 v38, 4, v2
	v_mov_b32_e32 v39, v141
	v_lshlrev_b32_e32 v40, 2, v4
	v_mov_b32_e32 v41, v141
	v_lshlrev_b32_e32 v42, 2, v6
	v_mov_b32_e32 v43, v141
	v_lshlrev_b32_e32 v44, 2, v8
	v_mov_b32_e32 v45, v141
	v_lshlrev_b32_e32 v46, 2, v10
	v_mov_b32_e32 v47, v141
	v_readlane_b32 s38, v236, 23
	v_readlane_b32 s39, v236, 24
	v_readlane_b32 s42, v236, 27
	v_readlane_b32 s43, v236, 28
	v_readlane_b32 s44, v236, 29
	v_readlane_b32 s45, v236, 30
	v_readlane_b32 s46, v236, 31
	v_readlane_b32 s47, v236, 32
	v_readlane_b32 s50, v236, 35
.LBB0_333:
	v_cmp_gt_i32_e32 vcc, s94, v55
	v_add_u32_e32 v0, 0xffff8000, v36
	v_ashrrev_i32_e32 v37, 31, v36
	v_cndmask_b32_e32 v1, 0, v37, vcc
	v_cndmask_b32_e32 v0, v0, v36, vcc
	v_cndmask_b32_e32 v3, v71, v72, vcc
	v_cndmask_b32_e32 v2, v73, v74, vcc
	v_lshlrev_b64 v[0:1], 12, v[0:1]
	v_add_u32_e32 v48, 1, v36
	v_lshl_add_u64 v[0:1], v[2:3], 0, v[0:1]
	v_cmp_gt_i32_e32 vcc, s93, v48
	v_ashrrev_i32_e32 v2, 31, v48
	v_add_u32_e32 v3, 0xffff8001, v36
	v_cndmask_b32_e32 v49, 0, v2, vcc
	v_cndmask_b32_e32 v2, v3, v48, vcc
	v_mov_b32_e32 v3, v49
	v_cndmask_b32_e32 v5, v71, v72, vcc
	v_cndmask_b32_e32 v4, v73, v74, vcc
	v_lshlrev_b64 v[2:3], 12, v[2:3]
	v_lshl_add_u64 v[2:3], v[4:5], 0, v[2:3]
	v_lshl_add_u64 v[0:1], v[0:1], 0, v[38:39]
	v_lshl_add_u64 v[2:3], v[2:3], 0, v[38:39]
	global_load_dwordx4 v[28:31], v[0:1], off nt
	global_load_dwordx4 v[12:15], v[2:3], off nt
	global_load_dwordx4 v[24:27], v[0:1], off offset:1024 nt
	global_load_dwordx4 v[8:11], v[2:3], off offset:1024 nt
	global_load_dwordx4 v[20:23], v[0:1], off offset:2048 nt
	global_load_dwordx4 v[4:7], v[2:3], off offset:2048 nt
	global_load_dwordx4 v[16:19], v[0:1], off offset:3072 nt
	s_nop 0
	global_load_dwordx4 v[0:3], v[2:3], off offset:3072 nt
	v_min_i32_e32 v50, 0x4000, v55
	v_ashrrev_i32_e32 v50, 11, v50
	v_mul_i32_i24_e32 v50, 0x1800, v50
	v_ashrrev_i32_e32 v51, 31, v50
	v_lshl_add_u64 v[50:51], v[50:51], 2, s[12:13]
	v_lshl_add_u64 v[52:53], v[50:51], 0, s[80:81]
	v_lshl_add_u64 v[62:63], v[52:53], 0, v[40:41]
	v_lshl_add_u64 v[50:51], v[50:51], 0, v[40:41]
	v_lshl_add_u64 v[60:61], v[52:53], 0, v[42:43]
	v_lshl_add_u64 v[56:57], v[52:53], 0, v[44:45]
	v_lshl_add_u64 v[52:53], v[52:53], 0, v[46:47]
	s_waitcnt vmcnt(7)
	v_mov_b32_e32 v76, v29
	v_mov_b32_e32 v64, v28
	s_waitcnt vmcnt(5)
	v_mov_b32_e32 v77, v25
	v_mov_b32_e32 v65, v24
	v_pk_mul_f32 v[76:77], v[76:77], v[76:77]
	v_mov_b32_e32 v78, v13
	v_pk_fma_f32 v[64:65], v[64:65], v[64:65], v[76:77]
	v_mov_b32_e32 v76, v30
	v_mov_b32_e32 v77, v26
	v_pk_fma_f32 v[64:65], v[76:77], v[76:77], v[64:65]
	v_mov_b32_e32 v76, v31
	v_mov_b32_e32 v77, v27
	s_waitcnt vmcnt(4)
; DI unsigned pack2(float lo, float hi) { f32x2_t v = {lo, hi}; bf16x2_t r = __builtin_convertvector(v, bf16x2_t); return __builtin_bit_cast(unsigned, r); }
; DI void phase_norm(const Params& p, int layer, int which  , int nrows) {
;     ...
;     }
; #pragma unroll
;     for (int i = 0; i < 4; ++i) {
;       ss0 += v[0][i].x * v[0][i].x + v[0][i].y * v[0][i].y + v[0][i].z * v[0][i].z + v[0][i].w * v[0][i].w;
;       ss1 += v[1][i].x * v[1][i].x + v[1][i].y * v[1][i].y + v[1][i].z * v[1][i].z + v[1][i].w * v[1][i].w;
;     }
;     ss0 = wave_sum(ss0); ss1 = wave_sum(ss1);
;     const float rstd0 = rsqrtf(ss0 * (1.0f / D) + 1e-6f), rstd1 = rsqrtf(ss1 * (1.0f / D) + 1e-6f);
; #pragma unroll
;     for (int k = 0; k < 2; ++k) {
;       const float rstd = k == 0 ? rstd0 : rstd1;
; #pragma unroll
;       for (int i = 0; i < 4; ++i) {
;         const int col = 4 * (lane + 64 * i);
;         float y0 = v[k][i].x * rstd * gg[i].x * (1.f + s4[i].x) + h4[i].x;
;         float y1 = v[k][i].y * rstd * gg[i].y * (1.f + s4[i].y) + h4[i].y;
;         float y2 = v[k][i].z * rstd * gg[i].z * (1.f + s4[i].z) + h4[i].z;
;         float y3 = v[k][i].w * rstd * gg[i].w * (1.f + s4[i].w) + h4[i].w;
;         uint2 w; w.x = pack2(y0, y1); w.y = pack2(y2, y3);
	v_mov_b32_e32 v79, v9
	v_pk_fma_f32 v[64:65], v[76:77], v[76:77], v[64:65]
	v_mov_b32_e32 v76, v12
	v_mov_b32_e32 v77, v8
	v_pk_mul_f32 v[78:79], v[78:79], v[78:79]
	s_waitcnt vmcnt(3)
	v_mov_b32_e32 v80, v21
	v_pk_fma_f32 v[76:77], v[76:77], v[76:77], v[78:79]
	v_mov_b32_e32 v78, v14
	v_mov_b32_e32 v79, v10
	v_pk_fma_f32 v[76:77], v[78:79], v[78:79], v[76:77]
	v_mov_b32_e32 v78, v15
	v_mov_b32_e32 v79, v11
	s_waitcnt vmcnt(1)
	v_mov_b32_e32 v81, v17
	v_pk_fma_f32 v[76:77], v[78:79], v[78:79], v[76:77]
	v_mov_b32_e32 v78, v20
	v_mov_b32_e32 v79, v16
	v_pk_mul_f32 v[80:81], v[80:81], v[80:81]
	v_mov_b32_e32 v82, v5
	v_pk_fma_f32 v[78:79], v[78:79], v[78:79], v[80:81]
	v_mov_b32_e32 v80, v22
	v_mov_b32_e32 v81, v18
	v_pk_fma_f32 v[78:79], v[80:81], v[80:81], v[78:79]
	v_mov_b32_e32 v80, v23
	v_mov_b32_e32 v81, v19
	s_waitcnt vmcnt(0)
	v_mov_b32_e32 v83, v1
	v_pk_fma_f32 v[78:79], v[80:81], v[80:81], v[78:79]
	v_mov_b32_e32 v80, v4
	v_mov_b32_e32 v81, v0
	v_pk_mul_f32 v[82:83], v[82:83], v[82:83]
	s_nop 0
	v_pk_fma_f32 v[80:81], v[80:81], v[80:81], v[82:83]
	v_mov_b32_e32 v82, v6
	v_mov_b32_e32 v83, v2
	v_pk_fma_f32 v[80:81], v[82:83], v[82:83], v[80:81]
	v_mov_b32_e32 v82, v7
	v_mov_b32_e32 v83, v3
	v_pk_fma_f32 v[80:81], v[82:83], v[82:83], v[80:81]
	v_mov_b32_e32 v82, v76
	v_mov_b32_e32 v83, v64
	v_mov_b32_e32 v64, v77
	v_pk_add_f32 v[64:65], v[82:83], v[64:65]
	v_mov_b32_e32 v76, v80
	v_mov_b32_e32 v77, v78
	v_pk_add_f32 v[64:65], v[64:65], v[76:77]
	v_mov_b32_e32 v78, v81
	v_pk_add_f32 v[64:65], v[64:65], v[78:79]
	ds_bpermute_b32 v77, v59, v65
	ds_bpermute_b32 v76, v59, v64
	s_waitcnt lgkmcnt(0)
	v_pk_add_f32 v[64:65], v[64:65], v[76:77]
	ds_bpermute_b32 v77, v66, v65
	ds_bpermute_b32 v76, v66, v64
	s_waitcnt lgkmcnt(0)
	v_pk_add_f32 v[64:65], v[64:65], v[76:77]
	ds_bpermute_b32 v77, v67, v65
	ds_bpermute_b32 v76, v67, v64
	s_waitcnt lgkmcnt(0)
	v_pk_add_f32 v[64:65], v[64:65], v[76:77]
	ds_bpermute_b32 v77, v68, v65
	ds_bpermute_b32 v76, v68, v64
	s_waitcnt lgkmcnt(0)
	v_pk_add_f32 v[64:65], v[64:65], v[76:77]
	ds_bpermute_b32 v77, v69, v65
	ds_bpermute_b32 v76, v69, v64
	s_waitcnt lgkmcnt(0)
	v_pk_add_f32 v[64:65], v[64:65], v[76:77]
	ds_bpermute_b32 v77, v70, v65
	ds_bpermute_b32 v76, v70, v64
	s_waitcnt lgkmcnt(0)
	v_pk_add_f32 v[64:65], v[64:65], v[76:77]
	global_load_dwordx4 v[76:79], v[32:33], off
	global_load_dwordx4 v[80:83], v[62:63], off
	global_load_dwordx4 v[84:87], v[50:51], off
	v_pk_fma_f32 v[64:65], v[64:65], s[52:53], v[142:143] op_sel_hi:[1,0,0]
	s_waitcnt vmcnt(1)
	v_pk_add_f32 v[92:93], v[80:81], 1.0 op_sel_hi:[1,0]
	v_mul_f32_e32 v54, 0x4b800000, v65
	v_cmp_gt_f32_e64 s[0:1], s15, v65
	v_pk_add_f32 v[94:95], v[82:83], 1.0 op_sel_hi:[1,0]
	v_cmp_gt_f32_e32 vcc, s15, v64
	v_cndmask_b32_e64 v54, v65, v54, s[0:1]
	v_rsq_f32_e32 v54, v54
	s_nop 0
	v_mul_f32_e32 v58, 0x45800000, v54
	v_cndmask_b32_e64 v58, v54, v58, s[0:1]
	v_pk_mul_f32 v[28:29], v[28:29], v[58:59] op_sel_hi:[1,0]
	v_pk_mul_f32 v[30:31], v[30:31], v[58:59] op_sel_hi:[1,0]
	v_pk_mul_f32 v[28:29], v[76:77], v[28:29]
	v_pk_mul_f32 v[30:31], v[78:79], v[30:31]
	s_waitcnt vmcnt(0)
	v_pk_fma_f32 v[28:29], v[92:93], v[28:29], v[84:85]
	v_pk_fma_f32 v[30:31], v[94:95], v[30:31], v[86:87]
	v_cvt_pk_bf16_f32 v96, v28, v29
	v_cvt_pk_bf16_f32 v97, v30, v31
	global_load_dwordx4 v[28:31], v[32:33], off offset:1024
	s_nop 0
	global_load_dwordx4 v[60:63], v[60:61], off
	s_nop 0
	global_load_dwordx4 v[80:83], v[50:51], off offset:1024
	v_pk_mul_f32 v[24:25], v[24:25], v[58:59] op_sel_hi:[1,0]
	v_pk_mul_f32 v[26:27], v[26:27], v[58:59] op_sel_hi:[1,0]
	v_pk_mul_f32 v[20:21], v[20:21], v[58:59] op_sel_hi:[1,0]
	v_pk_mul_f32 v[22:23], v[22:23], v[58:59] op_sel_hi:[1,0]
	v_mul_f32_e32 v54, 0x4b800000, v64
	v_cndmask_b32_e32 v54, v64, v54, vcc
	v_rsq_f32_e32 v54, v54
	v_pk_mul_f32 v[16:17], v[16:17], v[58:59] op_sel_hi:[1,0]
	v_pk_mul_f32 v[18:19], v[18:19], v[58:59] op_sel_hi:[1,0]
	v_mul_f32_e32 v64, 0x45800000, v54
	v_cndmask_b32_e32 v54, v54, v64, vcc
	v_lshlrev_b64 v[64:65], 11, v[36:37]
	v_pk_mul_f32 v[12:13], v[12:13], v[54:55] op_sel_hi:[1,0]
	v_pk_mul_f32 v[14:15], v[14:15], v[54:55] op_sel_hi:[1,0]
	v_pk_mul_f32 v[8:9], v[8:9], v[54:55] op_sel_hi:[1,0]
	v_pk_mul_f32 v[10:11], v[10:11], v[54:55] op_sel_hi:[1,0]
	v_pk_mul_f32 v[4:5], v[4:5], v[54:55] op_sel_hi:[1,0]
	v_pk_mul_f32 v[6:7], v[6:7], v[54:55] op_sel_hi:[1,0]
	v_pk_mul_f32 v[0:1], v[0:1], v[54:55] op_sel_hi:[1,0]
	v_pk_mul_f32 v[2:3], v[2:3], v[54:55] op_sel_hi:[1,0]
	v_lshl_add_u64 v[64:65], v[34:35], 0, v[64:65]
	v_pk_mul_f32 v[12:13], v[76:77], v[12:13]
	v_pk_mul_f32 v[14:15], v[78:79], v[14:15]
	v_add_u32_e32 v55, s53, v55
	v_pk_fma_f32 v[12:13], v[92:93], v[12:13], v[84:85]
	v_pk_fma_f32 v[14:15], v[94:95], v[14:15], v[86:87]
	v_cmp_lt_i32_e32 vcc, s95, v55
	v_cvt_pk_bf16_f32 v12, v12, v13
	v_cvt_pk_bf16_f32 v13, v14, v15
	v_add_u32_e32 v36, s54, v36
	s_or_b64 s[36:37], vcc, s[36:37]
	s_waitcnt vmcnt(2)
; DI unsigned pack2(float lo, float hi) { f32x2_t v = {lo, hi}; bf16x2_t r = __builtin_convertvector(v, bf16x2_t); return __builtin_bit_cast(unsigned, r); }
; DI void phase_norm(const Params& p, int layer, int which  , int nrows) {
;     ...
;     for (int k = 0; k < 2; ++k) {
;       const float rstd = k == 0 ? rstd0 : rstd1;
; #pragma unroll
;       for (int i = 0; i < 4; ++i) {
;         const int col = 4 * (lane + 64 * i);
;         float y0 = v[k][i].x * rstd * gg[i].x * (1.f + s4[i].x) + h4[i].x;
;         float y1 = v[k][i].y * rstd * gg[i].y * (1.f + s4[i].y) + h4[i].y;
;         float y2 = v[k][i].z * rstd * gg[i].z * (1.f + s4[i].z) + h4[i].z;
;         float y3 = v[k][i].w * rstd * gg[i].w * (1.f + s4[i].w) + h4[i].w;
;         uint2 w; w.x = pack2(y0, y1); w.y = pack2(y2, y3);
;         *(uint2*)(H + (size_t)(row + k) * D + col) = w;
;       }
	v_pk_mul_f32 v[24:25], v[28:29], v[24:25]
	s_waitcnt vmcnt(1)
	v_pk_add_f32 v[98:99], v[60:61], 1.0 op_sel_hi:[1,0]
	v_pk_mul_f32 v[26:27], v[30:31], v[26:27]
	v_pk_add_f32 v[100:101], v[62:63], 1.0 op_sel_hi:[1,0]
	s_waitcnt vmcnt(0)
	v_pk_fma_f32 v[24:25], v[98:99], v[24:25], v[80:81]
	v_pk_fma_f32 v[26:27], v[100:101], v[26:27], v[82:83]
	v_cvt_pk_bf16_f32 v102, v24, v25
	v_cvt_pk_bf16_f32 v103, v26, v27
	global_load_dwordx4 v[24:27], v[32:33], off offset:2048
	global_load_dwordx4 v[60:63], v[56:57], off
	global_load_dwordx4 v[88:91], v[50:51], off offset:2048
	v_pk_mul_f32 v[8:9], v[28:29], v[8:9]
	v_pk_mul_f32 v[10:11], v[30:31], v[10:11]
	v_pk_fma_f32 v[8:9], v[98:99], v[8:9], v[80:81]
	v_pk_fma_f32 v[10:11], v[100:101], v[10:11], v[82:83]
	v_cvt_pk_bf16_f32 v8, v8, v9
	v_cvt_pk_bf16_f32 v9, v10, v11
	s_waitcnt vmcnt(2)
	v_pk_mul_f32 v[20:21], v[24:25], v[20:21]
	s_waitcnt vmcnt(1)
	v_pk_add_f32 v[56:57], v[60:61], 1.0 op_sel_hi:[1,0]
	v_pk_mul_f32 v[22:23], v[26:27], v[22:23]
	v_pk_add_f32 v[104:105], v[62:63], 1.0 op_sel_hi:[1,0]
	s_waitcnt vmcnt(0)
	v_pk_fma_f32 v[20:21], v[56:57], v[20:21], v[88:89]
	v_pk_fma_f32 v[22:23], v[104:105], v[22:23], v[90:91]
	v_cvt_pk_bf16_f32 v106, v20, v21
	v_cvt_pk_bf16_f32 v107, v22, v23
	global_load_dwordx4 v[20:23], v[32:33], off offset:3072
	global_load_dwordx4 v[60:63], v[52:53], off
	s_nop 0
	global_load_dwordx4 v[50:53], v[50:51], off offset:3072
	v_pk_mul_f32 v[4:5], v[24:25], v[4:5]
	v_pk_mul_f32 v[6:7], v[26:27], v[6:7]
	v_sub_u32_e32 v166, v64, v162
	v_lshrrev_b32_e32 v166, 5, v166
	v_lshl_add_u64 v[144:145], v[166:167], 0, v[160:161]
	v_lshl_add_u64 v[146:147], v[144:145], 0, v[164:165]
	v_lshl_add_u64 v[148:149], v[146:147], 0, v[164:165]
	v_lshl_add_u64 v[150:151], v[148:149], 0, v[164:165]
	global_store_dwordx2 v[144:145], v[96:97], off
	global_store_dwordx2 v[146:147], v[102:103], off
	global_store_dwordx2 v[148:149], v[106:107], off
	v_pk_fma_f32 v[4:5], v[56:57], v[4:5], v[88:89]
	v_pk_fma_f32 v[6:7], v[104:105], v[6:7], v[90:91]
	v_cvt_pk_bf16_f32 v4, v4, v5
	v_cvt_pk_bf16_f32 v5, v6, v7
	s_waitcnt vmcnt(5)
	v_pk_mul_f32 v[16:17], v[20:21], v[16:17]
	s_waitcnt vmcnt(4)
	v_pk_add_f32 v[60:61], v[60:61], 1.0 op_sel_hi:[1,0]
	v_pk_mul_f32 v[18:19], v[22:23], v[18:19]
	v_pk_add_f32 v[62:63], v[62:63], 1.0 op_sel_hi:[1,0]
	s_waitcnt vmcnt(3)
	v_pk_fma_f32 v[16:17], v[60:61], v[16:17], v[50:51]
	v_pk_fma_f32 v[18:19], v[62:63], v[18:19], v[52:53]
	v_cvt_pk_bf16_f32 v16, v16, v17
	v_cvt_pk_bf16_f32 v17, v18, v19
	v_pk_mul_f32 v[0:1], v[20:21], v[0:1]
	v_pk_mul_f32 v[2:3], v[22:23], v[2:3]
	global_store_dwordx2 v[150:151], v[16:17], off
	v_lshlrev_b64 v[16:17], 11, v[48:49]
	v_pk_fma_f32 v[0:1], v[60:61], v[0:1], v[50:51]
	v_pk_fma_f32 v[2:3], v[62:63], v[2:3], v[52:53]
	v_lshl_add_u64 v[14:15], v[34:35], 0, v[16:17]
	v_cvt_pk_bf16_f32 v0, v0, v1
	v_cvt_pk_bf16_f32 v1, v2, v3
	v_sub_u32_e32 v174, v14, v162
	v_lshrrev_b32_e32 v174, 5, v174
	v_lshl_add_u64 v[152:153], v[174:175], 0, v[160:161]
	v_lshl_add_u64 v[154:155], v[152:153], 0, v[164:165]
	v_lshl_add_u64 v[156:157], v[154:155], 0, v[164:165]
	v_lshl_add_u64 v[158:159], v[156:157], 0, v[164:165]
	global_store_dwordx2 v[152:153], v[12:13], off
	global_store_dwordx2 v[154:155], v[8:9], off
	global_store_dwordx2 v[156:157], v[4:5], off
	global_store_dwordx2 v[158:159], v[0:1], off
	s_andn2_b64 exec, exec, s[36:37]
	s_cbranch_execnz .LBB0_333

; DI int get_tid() { int t = threadIdx.x; asm volatile("" : "+v"(t)); return t; }
; DI void phase_norm(const Params& p, int layer, int which  , int nrows) {
;   const int lane = get_tid() & 63, gw = blockIdx.x * 4 + (get_tid() >> 6), nw = gridDim.x * 4;
;   const float* g = (which == 0 ? p.norm1_g : p.norm2_g) + layer * D;
;   const float* mod = (const float*)(p.ws + OFF_MOD) + (size_t)layer * 9 * 6144;
;   bf16_t* H = (bf16_t*)(p.ws + OFF_H);
;   const bool first = (which == 0) && layer == 0;
;   for (int pr = gw; pr < (nrows >> 1); pr += nw) {
;     const int row = pr * 2;
;     const float* xr0 = xold_ptr(p, layer, first, row);
;     const float* xr1 = xold_ptr(p, layer, first, row + 1);
;     const int b9 = row < NLAT ? (row >> 12) : 8;
;     float4 v[2][4];
;     float ss0 = 0.f, ss1 = 0.f;
; #pragma unroll
;     for (int i = 0; i < 4; ++i) {
;       typedef float f4ld __attribute__((ext_vector_type(4)));
;       const f4ld a_ = __builtin_nontemporal_load((const f4ld*)xr0 + lane + 64 * i), b_ = __builtin_nontemporal_load((const f4ld*)xr1 + lane + 64 * i);
;       v[0][i] = make_float4(a_[0], a_[1], a_[2], a_[3]); v[1][i] = make_float4(b_[0], b_[1], b_[2], b_[3]);
;     }
;     const float* sh = mod + b9 * 6144 + (which == 0 ? 0 : 3) * 1024;
;     const float* sc = sh + 1024;
;     float4 gg[4], s4[4], h4[4];
; #pragma unroll
;     for (int i = 0; i < 4; ++i) {
;       const int col = 4 * (lane + 64 * i);
;       gg[i] = *(const float4*)(g + col); s4[i] = *(const float4*)(sc + col); h4[i] = *(const float4*)(sh + col);
;     }
; #pragma unroll
;     for (int i = 0; i < 4; ++i) {
;       ss0 += v[0][i].x * v[0][i].x + v[0][i].y * v[0][i].y + v[0][i].z * v[0][i].z + v[0][i].w * v[0][i].w;
;       ss1 += v[1][i].x * v[1][i].x + v[1][i].y * v[1][i].y + v[1][i].z * v[1][i].z + v[1][i].w * v[1][i].w;
;     }
;     ss0 = wave_sum(ss0); ss1 = wave_sum(ss1);
.LBB0_1594:
	s_or_b64 exec, exec, s[0:1]
	v_and_b32_e32 v168, 63, v143
	v_lshlrev_b32_e32 v169, 3, v168
	v_add_u32_e32 v162, s24, v169
	v_add_u32_e32 v162, 0x15980000, v162
	v_lshrrev_b32_e32 v170, 3, v168
	v_mul_u32_u24_e32 v170, 0x220000, v170
	v_and_b32_e32 v171, 7, v168
	v_lshl_add_u32 v170, v171, 3, v170
	v_mov_b32_e32 v171, 0
	v_mov_b32_e32 v160, s24
	v_mov_b32_e32 v161, s25
	v_mov_b32_e32 v172, 0x15980000
	v_mov_b32_e32 v173, 0
	v_lshl_add_u64 v[160:161], v[160:161], 0, v[172:173]
	v_lshl_add_u64 v[160:161], v[160:161], 0, v[170:171]
	v_mov_b32_e32 v164, 0x1100000
	v_mov_b32_e32 v165, 0
	v_mov_b32_e32 v167, 0
	v_mov_b32_e32 v175, 0
	v_mov_b32_e32 v1, v143
	s_waitcnt lgkmcnt(0)
	v_mov_b32_e32 v0, v143
	s_barrier
	s_lshl_b32 s28, s46, 6
	v_ashrrev_i32_e32 v0, 6, v0
	v_add_u32_e32 v53, s34, v0
	v_cmp_gt_i32_e32 vcc, s28, v53
	s_and_saveexec_b64 s[10:11], vcc
	s_movk_i32 s29, 0x4000
	s_mov_b64 s[38:39], 0x1000
	s_cbranch_execz .LBB0_1597
	v_readlane_b32 s76, v236, 21
	v_readlane_b32 s88, v236, 33
	v_readlane_b32 s89, v236, 34
	s_lshl_b32 s0, s52, 10
	s_mov_b32 s1, s92
	v_readlane_b32 s90, v236, 35
	v_readlane_b32 s91, v236, 36
	s_mov_b32 s12, s51
	s_mov_b64 s[48:49], s[88:89]
	s_lshl_b64 s[0:1], s[0:1], 2
	s_mov_b64 s[50:51], s[90:91]
	s_add_u32 s0, s50, s0
	v_readlane_b32 s77, v236, 22
	v_readlane_b32 s78, v236, 23
	v_readlane_b32 s79, v236, 24
	v_readlane_b32 s80, v236, 25
	v_readlane_b32 s81, v236, 26
	v_readlane_b32 s82, v236, 27
	v_readlane_b32 s83, v236, 28
	v_readlane_b32 s84, v236, 29
	v_readlane_b32 s85, v236, 30
	v_readlane_b32 s86, v236, 31
	v_readlane_b32 s87, v236, 32
	s_addc_u32 s1, s51, s1
	s_mov_b32 s51, s12
	v_readlane_b32 s12, v234, 46
	v_cmp_lt_i32_e32 vcc, v202, v196
	v_readlane_b32 s78, v234, 27
	v_readlane_b32 s90, v234, 25
	v_readlane_b32 s76, v234, 44
	v_readlane_b32 s88, v234, 42
	v_readlane_b32 s86, v234, 40
	v_readlane_b32 s84, v234, 38
	v_readlane_b32 s82, v234, 36
	v_readlane_b32 s80, v234, 34
	v_readlane_b32 s13, v234, 47
	v_and_b32_e32 v2, 63, v1
	v_cndmask_b32_e32 v1, v195, v202, vcc
	v_cmp_lt_i32_e32 vcc, v201, v196
	v_readlane_b32 s79, v234, 28
	v_readlane_b32 s91, v234, 26
	v_readlane_b32 s77, v234, 45
	v_readlane_b32 s89, v234, 43
	v_readlane_b32 s87, v234, 41
	v_readlane_b32 s85, v234, 39
	v_readlane_b32 s83, v234, 37
	v_readlane_b32 s81, v234, 35
	v_readlane_b32 s14, v234, 33
	s_mov_b32 s36, s12
	s_mov_b32 s37, s92
	v_writelane_b32 v234, s12, 46
	v_lshlrev_b32_e32 v57, 2, v1
	v_cndmask_b32_e32 v1, v195, v201, vcc
	v_cmp_lt_i32_e32 vcc, v200, v196
	v_writelane_b32 v234, s13, 47
	s_lshl_b64 s[12:13], s[36:37], 2
	v_readlane_b32 s36, v236, 38
	s_waitcnt vmcnt(0)
	v_lshlrev_b32_e32 v64, 2, v1
	v_cndmask_b32_e32 v1, v195, v200, vcc
	v_cmp_lt_i32_e32 vcc, v199, v196
	v_readlane_b32 s37, v236, 39
	s_add_u32 s12, s36, s12
	v_lshlrev_b32_e32 v65, 2, v1
	v_cndmask_b32_e32 v1, v195, v199, vcc
	v_cmp_lt_i32_e32 vcc, v198, v196
	s_addc_u32 s13, s37, s13
	v_lshlrev_b32_e32 v4, 2, v2
	v_lshlrev_b32_e32 v66, 2, v1
	v_cndmask_b32_e32 v1, v195, v198, vcc
	v_cmp_lt_i32_e32 vcc, v197, v196
	v_lshlrev_b32_e32 v6, 4, v2
	v_mov_b32_e32 v7, v141
	s_add_u32 s12, s12, 0x3000
	v_lshlrev_b32_e32 v67, 2, v1
	v_cndmask_b32_e32 v1, v195, v197, vcc
	v_lshl_add_u64 v[32:33], s[0:1], 0, v[6:7]
	v_or_b32_e32 v6, 0x100, v4
	v_or_b32_e32 v8, 0x200, v4
	v_or_b32_e32 v10, 0x300, v4
	v_lshlrev_b32_e32 v12, 3, v2
	v_mov_b32_e32 v13, v141
	v_readlane_b32 s0, v234, 14
	s_mov_b32 s40, 0x3a800000
	s_addc_u32 s13, s13, 0
	v_lshlrev_b32_e32 v68, 2, v1
	v_lshl_add_u64 v[34:35], s[74:75], 0, v[12:13]
	v_lshl_add_u32 v36, v0, 1, s0
	s_mov_b64 s[36:37], 0
	v_lshlrev_b32_e32 v140, 4, v2
	v_lshlrev_b32_e32 v38, 2, v4
	v_lshlrev_b32_e32 v40, 2, v6
	v_lshlrev_b32_e32 v42, 2, v8
	v_lshlrev_b32_e32 v44, 2, v10
.LBB0_1596:
	v_cmp_gt_i32_e32 vcc, s29, v53
	v_add_u32_e32 v0, 0xffff8000, v36
	v_ashrrev_i32_e32 v37, 31, v36
	v_cndmask_b32_e32 v1, 0, v37, vcc
	v_cndmask_b32_e32 v0, v0, v36, vcc
	v_mov_b32_e32 v4, s14
	v_mov_b32_e32 v5, s23
	v_mov_b32_e32 v6, s35
	v_mov_b32_e32 v7, s22
	v_cndmask_b32_e32 v3, v4, v5, vcc
	v_cndmask_b32_e32 v2, v6, v7, vcc
	v_lshlrev_b64 v[0:1], 12, v[0:1]
	v_add_u32_e32 v46, 1, v36
	v_lshl_add_u64 v[0:1], v[2:3], 0, v[0:1]
	v_cmp_gt_i32_e32 vcc, s30, v46
	v_ashrrev_i32_e32 v2, 31, v46
	v_add_u32_e32 v3, 0xffff8001, v36
	v_cndmask_b32_e32 v47, 0, v2, vcc
	v_cndmask_b32_e32 v2, v3, v46, vcc
	v_mov_b32_e32 v3, v47
	v_cndmask_b32_e32 v5, v4, v5, vcc
	v_cndmask_b32_e32 v4, v6, v7, vcc
	v_lshlrev_b64 v[2:3], 12, v[2:3]
	v_lshl_add_u64 v[2:3], v[4:5], 0, v[2:3]
	v_lshl_add_u64 v[0:1], v[0:1], 0, v[140:141]
	v_lshl_add_u64 v[2:3], v[2:3], 0, v[140:141]
	global_load_dwordx4 v[28:31], v[0:1], off nt
	global_load_dwordx4 v[12:15], v[2:3], off nt
	global_load_dwordx4 v[24:27], v[0:1], off offset:1024 nt
	global_load_dwordx4 v[8:11], v[2:3], off offset:1024 nt
	global_load_dwordx4 v[20:23], v[0:1], off offset:2048 nt
	global_load_dwordx4 v[4:7], v[2:3], off offset:2048 nt
	global_load_dwordx4 v[16:19], v[0:1], off offset:3072 nt
	s_nop 0
	global_load_dwordx4 v[0:3], v[2:3], off offset:3072 nt
	v_min_i32_e32 v39, 0x4000, v53
	v_ashrrev_i32_e32 v39, 11, v39
	v_mul_i32_i24_e32 v48, 0x1800, v39
	v_ashrrev_i32_e32 v49, 31, v48
	v_lshl_add_u64 v[48:49], v[48:49], 2, s[12:13]
	v_lshl_add_u64 v[50:51], v[48:49], 0, s[38:39]
	v_mov_b32_e32 v39, v141
	v_lshl_add_u64 v[60:61], v[50:51], 0, v[38:39]
	v_lshl_add_u64 v[48:49], v[48:49], 0, v[38:39]
	v_mov_b32_e32 v41, v141
	v_lshl_add_u64 v[58:59], v[50:51], 0, v[40:41]
	v_mov_b32_e32 v43, v141
	v_lshl_add_u64 v[54:55], v[50:51], 0, v[42:43]
	v_mov_b32_e32 v45, v141
	v_lshl_add_u64 v[50:51], v[50:51], 0, v[44:45]
	s_waitcnt vmcnt(7)
; DI void phase_norm(const Params& p, int layer, int which  , int nrows) {
;     ...
;       ss0 += v[0][i].x * v[0][i].x + v[0][i].y * v[0][i].y + v[0][i].z * v[0][i].z + v[0][i].w * v[0][i].w;
;       ss1 += v[1][i].x * v[1][i].x + v[1][i].y * v[1][i].y + v[1][i].z * v[1][i].z + v[1][i].w * v[1][i].w;
;     }
;     ss0 = wave_sum(ss0); ss1 = wave_sum(ss1);
;     const float rstd0 = rsqrtf(ss0 * (1.0f / D) + 1e-6f), rstd1 = rsqrtf(ss1 * (1.0f / D) + 1e-6f);
	v_mov_b32_e32 v70, v29
	v_mov_b32_e32 v62, v28
	s_waitcnt vmcnt(5)
	v_mov_b32_e32 v71, v25
	v_mov_b32_e32 v63, v24
	v_pk_mul_f32 v[70:71], v[70:71], v[70:71]
	v_mov_b32_e32 v72, v13
	v_pk_fma_f32 v[62:63], v[62:63], v[62:63], v[70:71]
	v_mov_b32_e32 v70, v30
	v_mov_b32_e32 v71, v26
	v_pk_fma_f32 v[62:63], v[70:71], v[70:71], v[62:63]
	v_mov_b32_e32 v70, v31
	v_mov_b32_e32 v71, v27
	s_waitcnt vmcnt(4)
	v_mov_b32_e32 v73, v9
	v_pk_fma_f32 v[62:63], v[70:71], v[70:71], v[62:63]
	v_mov_b32_e32 v70, v12
	v_mov_b32_e32 v71, v8
	v_pk_mul_f32 v[72:73], v[72:73], v[72:73]
	s_waitcnt vmcnt(3)
	v_mov_b32_e32 v74, v21
	v_pk_fma_f32 v[70:71], v[70:71], v[70:71], v[72:73]
	v_mov_b32_e32 v72, v14
	v_mov_b32_e32 v73, v10
	v_pk_fma_f32 v[70:71], v[72:73], v[72:73], v[70:71]
	v_mov_b32_e32 v72, v15
	v_mov_b32_e32 v73, v11
	s_waitcnt vmcnt(1)
	v_mov_b32_e32 v75, v17
	v_pk_fma_f32 v[70:71], v[72:73], v[72:73], v[70:71]
	v_mov_b32_e32 v72, v20
	v_mov_b32_e32 v73, v16
	v_pk_mul_f32 v[74:75], v[74:75], v[74:75]
	v_mov_b32_e32 v76, v5
	v_pk_fma_f32 v[72:73], v[72:73], v[72:73], v[74:75]
	v_mov_b32_e32 v74, v22
	v_mov_b32_e32 v75, v18
	v_pk_fma_f32 v[72:73], v[74:75], v[74:75], v[72:73]
	v_mov_b32_e32 v74, v23
	v_mov_b32_e32 v75, v19
	s_waitcnt vmcnt(0)
	v_mov_b32_e32 v77, v1
	v_pk_fma_f32 v[72:73], v[74:75], v[74:75], v[72:73]
	v_mov_b32_e32 v74, v4
	v_mov_b32_e32 v75, v0
	v_pk_mul_f32 v[76:77], v[76:77], v[76:77]
	s_nop 0
	v_pk_fma_f32 v[74:75], v[74:75], v[74:75], v[76:77]
	v_mov_b32_e32 v76, v6
	v_mov_b32_e32 v77, v2
	v_pk_fma_f32 v[74:75], v[76:77], v[76:77], v[74:75]
	v_mov_b32_e32 v76, v7
	v_mov_b32_e32 v77, v3
	v_pk_fma_f32 v[74:75], v[76:77], v[76:77], v[74:75]
	v_mov_b32_e32 v76, v70
	v_mov_b32_e32 v77, v62
	v_mov_b32_e32 v62, v71
	v_pk_add_f32 v[62:63], v[76:77], v[62:63]
	v_mov_b32_e32 v70, v74
	v_mov_b32_e32 v71, v72
	v_pk_add_f32 v[62:63], v[62:63], v[70:71]
	v_mov_b32_e32 v72, v75
	v_pk_add_f32 v[62:63], v[62:63], v[72:73]
	ds_bpermute_b32 v71, v57, v63
	ds_bpermute_b32 v70, v57, v62
	s_waitcnt lgkmcnt(0)
	v_pk_add_f32 v[62:63], v[62:63], v[70:71]
	ds_bpermute_b32 v71, v64, v63
	ds_bpermute_b32 v70, v64, v62
	s_waitcnt lgkmcnt(0)
	v_pk_add_f32 v[62:63], v[62:63], v[70:71]
	ds_bpermute_b32 v71, v65, v63
	ds_bpermute_b32 v70, v65, v62
	s_waitcnt lgkmcnt(0)
	v_pk_add_f32 v[62:63], v[62:63], v[70:71]
	ds_bpermute_b32 v71, v66, v63
	ds_bpermute_b32 v70, v66, v62
	s_waitcnt lgkmcnt(0)
	v_pk_add_f32 v[62:63], v[62:63], v[70:71]
	ds_bpermute_b32 v71, v67, v63
	ds_bpermute_b32 v70, v67, v62
	s_waitcnt lgkmcnt(0)
	v_pk_add_f32 v[62:63], v[62:63], v[70:71]
	ds_bpermute_b32 v71, v68, v63
	ds_bpermute_b32 v70, v68, v62
	s_waitcnt lgkmcnt(0)
	v_pk_add_f32 v[62:63], v[62:63], v[70:71]
	global_load_dwordx4 v[70:73], v[32:33], off
	global_load_dwordx4 v[74:77], v[60:61], off
	global_load_dwordx4 v[78:81], v[48:49], off
	v_pk_fma_f32 v[62:63], v[62:63], s[40:41], v[142:143] op_sel_hi:[1,0,0]
	s_waitcnt vmcnt(1)
	v_pk_add_f32 v[86:87], v[74:75], 1.0 op_sel_hi:[1,0]
	v_mul_f32_e32 v39, 0x4b800000, v63
	v_cmp_gt_f32_e64 s[0:1], s15, v63
	v_pk_add_f32 v[88:89], v[76:77], 1.0 op_sel_hi:[1,0]
	v_cmp_gt_f32_e32 vcc, s15, v62
	v_cndmask_b32_e64 v39, v63, v39, s[0:1]
	v_rsq_f32_e32 v39, v39
	s_nop 0
	v_mul_f32_e32 v41, 0x45800000, v39
	v_cndmask_b32_e64 v56, v39, v41, s[0:1]
	v_pk_mul_f32 v[28:29], v[28:29], v[56:57] op_sel_hi:[1,0]
	v_pk_mul_f32 v[30:31], v[30:31], v[56:57] op_sel_hi:[1,0]
	v_pk_mul_f32 v[28:29], v[70:71], v[28:29]
	v_pk_mul_f32 v[30:31], v[72:73], v[30:31]
	s_waitcnt vmcnt(0)
; DI unsigned pack2(float lo, float hi) { f32x2_t v = {lo, hi}; bf16x2_t r = __builtin_convertvector(v, bf16x2_t); return __builtin_bit_cast(unsigned, r); }
; DI void phase_norm(const Params& p, int layer, int which  , int nrows) {
;     ...
;     for (int k = 0; k < 2; ++k) {
;       const float rstd = k == 0 ? rstd0 : rstd1;
; #pragma unroll
;       for (int i = 0; i < 4; ++i) {
;         const int col = 4 * (lane + 64 * i);
;         float y0 = v[k][i].x * rstd * gg[i].x * (1.f + s4[i].x) + h4[i].x;
;         float y1 = v[k][i].y * rstd * gg[i].y * (1.f + s4[i].y) + h4[i].y;
;         float y2 = v[k][i].z * rstd * gg[i].z * (1.f + s4[i].z) + h4[i].z;
;         float y3 = v[k][i].w * rstd * gg[i].w * (1.f + s4[i].w) + h4[i].w;
;         uint2 w; w.x = pack2(y0, y1); w.y = pack2(y2, y3);
;         *(uint2*)(H + (size_t)(row + k) * D + col) = w;
;       }
	v_pk_fma_f32 v[28:29], v[86:87], v[28:29], v[78:79]
	v_pk_fma_f32 v[30:31], v[88:89], v[30:31], v[80:81]
	v_cvt_pk_bf16_f32 v90, v28, v29
	v_cvt_pk_bf16_f32 v91, v30, v31
	global_load_dwordx4 v[28:31], v[32:33], off offset:1024
	s_nop 0
	global_load_dwordx4 v[58:61], v[58:59], off
	s_nop 0
	global_load_dwordx4 v[74:77], v[48:49], off offset:1024
	v_pk_mul_f32 v[24:25], v[24:25], v[56:57] op_sel_hi:[1,0]
	v_pk_mul_f32 v[26:27], v[26:27], v[56:57] op_sel_hi:[1,0]
	v_pk_mul_f32 v[20:21], v[20:21], v[56:57] op_sel_hi:[1,0]
	v_pk_mul_f32 v[22:23], v[22:23], v[56:57] op_sel_hi:[1,0]
	v_mul_f32_e32 v39, 0x4b800000, v62
	v_cndmask_b32_e32 v39, v62, v39, vcc
	v_rsq_f32_e32 v39, v39
	v_pk_mul_f32 v[16:17], v[16:17], v[56:57] op_sel_hi:[1,0]
	v_pk_mul_f32 v[18:19], v[18:19], v[56:57] op_sel_hi:[1,0]
	v_lshlrev_b64 v[62:63], 11, v[36:37]
	v_mul_f32_e32 v41, 0x45800000, v39
	v_cndmask_b32_e32 v52, v39, v41, vcc
	v_pk_mul_f32 v[12:13], v[12:13], v[52:53] op_sel_hi:[1,0]
	v_pk_mul_f32 v[14:15], v[14:15], v[52:53] op_sel_hi:[1,0]
	v_pk_mul_f32 v[8:9], v[8:9], v[52:53] op_sel_hi:[1,0]
	v_pk_mul_f32 v[10:11], v[10:11], v[52:53] op_sel_hi:[1,0]
	v_pk_mul_f32 v[4:5], v[4:5], v[52:53] op_sel_hi:[1,0]
	v_pk_mul_f32 v[6:7], v[6:7], v[52:53] op_sel_hi:[1,0]
	v_pk_mul_f32 v[0:1], v[0:1], v[52:53] op_sel_hi:[1,0]
	v_pk_mul_f32 v[2:3], v[2:3], v[52:53] op_sel_hi:[1,0]
	v_lshl_add_u64 v[62:63], v[34:35], 0, v[62:63]
	v_pk_mul_f32 v[12:13], v[70:71], v[12:13]
	v_pk_mul_f32 v[14:15], v[72:73], v[14:15]
	v_add_u32_e32 v53, s53, v53
	v_pk_fma_f32 v[12:13], v[86:87], v[12:13], v[78:79]
	v_pk_fma_f32 v[14:15], v[88:89], v[14:15], v[80:81]
	v_cmp_le_i32_e32 vcc, s28, v53
	v_cvt_pk_bf16_f32 v12, v12, v13
	v_cvt_pk_bf16_f32 v13, v14, v15
	v_add_u32_e32 v36, s54, v36
	s_or_b64 s[36:37], vcc, s[36:37]
	s_waitcnt vmcnt(2)
	v_pk_mul_f32 v[24:25], v[28:29], v[24:25]
	s_waitcnt vmcnt(1)
	v_pk_add_f32 v[92:93], v[58:59], 1.0 op_sel_hi:[1,0]
	v_pk_mul_f32 v[26:27], v[30:31], v[26:27]
	v_pk_add_f32 v[94:95], v[60:61], 1.0 op_sel_hi:[1,0]
	s_waitcnt vmcnt(0)
	v_pk_fma_f32 v[24:25], v[92:93], v[24:25], v[74:75]
	v_pk_fma_f32 v[26:27], v[94:95], v[26:27], v[76:77]
	v_cvt_pk_bf16_f32 v96, v24, v25
	v_cvt_pk_bf16_f32 v97, v26, v27
	global_load_dwordx4 v[24:27], v[32:33], off offset:2048
	global_load_dwordx4 v[58:61], v[54:55], off
	global_load_dwordx4 v[82:85], v[48:49], off offset:2048
	v_pk_mul_f32 v[8:9], v[28:29], v[8:9]
	v_pk_mul_f32 v[10:11], v[30:31], v[10:11]
	v_pk_fma_f32 v[8:9], v[92:93], v[8:9], v[74:75]
	v_pk_fma_f32 v[10:11], v[94:95], v[10:11], v[76:77]
	v_cvt_pk_bf16_f32 v8, v8, v9
	v_cvt_pk_bf16_f32 v9, v10, v11
	s_waitcnt vmcnt(2)
	v_pk_mul_f32 v[20:21], v[24:25], v[20:21]
	s_waitcnt vmcnt(1)
	v_pk_add_f32 v[54:55], v[58:59], 1.0 op_sel_hi:[1,0]
	v_pk_mul_f32 v[22:23], v[26:27], v[22:23]
	v_pk_add_f32 v[98:99], v[60:61], 1.0 op_sel_hi:[1,0]
	s_waitcnt vmcnt(0)
	v_pk_fma_f32 v[20:21], v[54:55], v[20:21], v[82:83]
	v_pk_fma_f32 v[22:23], v[98:99], v[22:23], v[84:85]
	v_cvt_pk_bf16_f32 v100, v20, v21
	v_cvt_pk_bf16_f32 v101, v22, v23
	global_load_dwordx4 v[20:23], v[32:33], off offset:3072
	global_load_dwordx4 v[58:61], v[50:51], off
	s_nop 0
	global_load_dwordx4 v[48:51], v[48:49], off offset:3072
	v_pk_mul_f32 v[4:5], v[24:25], v[4:5]
	v_pk_mul_f32 v[6:7], v[26:27], v[6:7]
	v_sub_u32_e32 v166, v62, v162
	v_lshrrev_b32_e32 v166, 5, v166
	v_lshl_add_u64 v[144:145], v[166:167], 0, v[160:161]
	v_lshl_add_u64 v[146:147], v[144:145], 0, v[164:165]
	v_lshl_add_u64 v[148:149], v[146:147], 0, v[164:165]
	v_lshl_add_u64 v[150:151], v[148:149], 0, v[164:165]
	global_store_dwordx2 v[144:145], v[90:91], off
	global_store_dwordx2 v[146:147], v[96:97], off
	global_store_dwordx2 v[148:149], v[100:101], off
	v_pk_fma_f32 v[4:5], v[54:55], v[4:5], v[82:83]
	v_pk_fma_f32 v[6:7], v[98:99], v[6:7], v[84:85]
	v_cvt_pk_bf16_f32 v4, v4, v5
	v_cvt_pk_bf16_f32 v5, v6, v7
	s_waitcnt vmcnt(5)
	v_pk_mul_f32 v[16:17], v[20:21], v[16:17]
	s_waitcnt vmcnt(4)
	v_pk_add_f32 v[58:59], v[58:59], 1.0 op_sel_hi:[1,0]
	v_pk_mul_f32 v[18:19], v[22:23], v[18:19]
	v_pk_add_f32 v[60:61], v[60:61], 1.0 op_sel_hi:[1,0]
	s_waitcnt vmcnt(3)
	v_pk_fma_f32 v[16:17], v[58:59], v[16:17], v[48:49]
	v_pk_fma_f32 v[18:19], v[60:61], v[18:19], v[50:51]
	v_cvt_pk_bf16_f32 v16, v16, v17
	v_cvt_pk_bf16_f32 v17, v18, v19
	v_pk_mul_f32 v[0:1], v[20:21], v[0:1]
	v_pk_mul_f32 v[2:3], v[22:23], v[2:3]
	global_store_dwordx2 v[150:151], v[16:17], off
	v_lshlrev_b64 v[16:17], 11, v[46:47]
	v_pk_fma_f32 v[0:1], v[58:59], v[0:1], v[48:49]
	v_pk_fma_f32 v[2:3], v[60:61], v[2:3], v[50:51]
	v_lshl_add_u64 v[14:15], v[34:35], 0, v[16:17]
	v_cvt_pk_bf16_f32 v0, v0, v1
	v_cvt_pk_bf16_f32 v1, v2, v3
	v_sub_u32_e32 v174, v14, v162
	v_lshrrev_b32_e32 v174, 5, v174
	v_lshl_add_u64 v[152:153], v[174:175], 0, v[160:161]
	v_lshl_add_u64 v[154:155], v[152:153], 0, v[164:165]
	v_lshl_add_u64 v[156:157], v[154:155], 0, v[164:165]
	v_lshl_add_u64 v[158:159], v[156:157], 0, v[164:165]
	global_store_dwordx2 v[152:153], v[12:13], off
	global_store_dwordx2 v[154:155], v[8:9], off
	global_store_dwordx2 v[156:157], v[4:5], off
	global_store_dwordx2 v[158:159], v[0:1], off
	s_andn2_b64 exec, exec, s[36:37]
	s_cbranch_execnz .LBB0_1596

; template <int EPI>
; DI void gemm_phase(const Params& p, int layer, const bf16_t* __restrict__ A, int lda, const bf16_t* __restrict__ Bt, int ldb, int K, int MT, int NT,
;                    char* smem, bool rev = false) {
;     ...
;   const bf16_t* Agl = A + (size_t)(m0 + lr) * lda + lc;
;   const bf16_t* Bgl = Bt + (size_t)(n0 + lr) * ldb + lc;
; __global__ void __launch_bounds__(THREADS, 2) fwd_megakernel(Params p) {
;     ...
;     gemm_phase<EPI_U>(p, layer, (const bf16_t*)(p.ws + OFF_H), D, wl + W_IN, D, D, MT_ALL, INP / 128, smem);
;     xcd_barrier(xb);
;     phase_prep(p, layer, smem);
;     xcd_barrier(xb);
;     phase_mix_a(p, layer, smem);
;     xcd_barrier(xb);
;     phase_attn(p, layer, smem);
;     xcd_barrier(xb);
;     gemm_phase<EPI_RES1>(p, layer, (const bf16_t*)(p.ws + OFF_U), D, wl + W_OUT, D, D, MT_RES, D / 128, smem);
;     xcd_barrier(xb);
;     phase_norm(p, layer, 1, MT_RES * 128);
;     xcd_barrier(xb);
;     gemm_phase<EPI_SWIGLU>(p, layer, (const bf16_t*)(p.ws + OFF_H), D, wl + W_13, D, D, MT_RES, 2 * FFH / 128, smem);
;     xcd_barrier(xb);
;     gemm_phase<EPI_RES2>(p, layer, (const bf16_t*)(p.ws + OFF_U), FFH, wl + W_2, FFH, FFH, MT_RES, D / 128, smem);
.Lmg_par_2:
	s_add_u32 s54, s24, 0x15980000
	s_addc_u32 s55, s25, 0
	s_movk_i32 s58, 0x40
	s_movk_i32 s59, 0x40
	s_mov_b32 s81, 0x220000
	s_mov_b32 s48, 0x1e000
	s_movk_i32 s60, 32
	s_movk_i32 s62, 15
	s_movk_i32 s69, 9363
	s_branch .Lmg_pare_6
.Lmg_par_3:
	s_mov_b32 s54, s24
	s_mov_b32 s55, s25
	s_movk_i32 s58, 0x800
	s_movk_i32 s59, 0x40
	s_mov_b32 s81, 0x40
	s_mov_b32 s48, 0x10000
	s_movk_i32 s60, 32
	s_movk_i32 s62, 8
	s_movk_i32 s69, 8192
	s_add_u32 s56, s56, 0x3c0000
	s_addc_u32 s57, s57, 0
	s_branch .Lmg_pare_6
.Lmg_par_4:
	s_add_u32 s54, s24, 0x15980000
	s_addc_u32 s55, s25, 0
	s_movk_i32 s58, 0x40
	s_movk_i32 s59, 0x40
	s_mov_b32 s81, 0x220000
	s_mov_b32 s48, 0x58000
	s_movk_i32 s60, 32
	s_movk_i32 s62, 44
	s_movk_i32 s69, 16384
	s_add_u32 s56, s56, 0x5c0000
	s_addc_u32 s57, s57, 0
	s_branch .Lmg_pare_6
.Lmg_par_5:
	s_mov_b32 s54, s24
	s_mov_b32 s55, s25
	s_movk_i32 s58, 0x40
	s_movk_i32 s59, 0x40
	s_mov_b32 s81, 0x220000
	s_mov_b32 s48, 0x10000
	s_movk_i32 s60, 88
	s_movk_i32 s62, 8
	s_movk_i32 s69, 8192
	s_add_u32 s56, s56, 0x10c0000
	s_addc_u32 s57, s57, 0

; template <int DQK>
; DI void attn_item(const bf16_t* __restrict__ Q, const bf16_t* __restrict__ Kp, const bf16_t* __restrict__ Vt, int q0, int nkeys,
;                   bf16_t* __restrict__ mix, int colbase, int b, char* smem) {
;     ...
;   bf16x8 qf[NSTEP];
;   {
;     const bf16_t* qr = Q + (size_t)(q0 + wave * 32 + r) * DQK + 8 * h;
; #pragma unroll
;     for (int s = 0; s < NSTEP; ++s) qf[s] = *(const bf16x8*)(qr + 16 * s);
;   }
;   const int kid0 = tid, kid1 = tid + 256, kid2 = tid + 512;
;   const int kgo0 = (kid0 / KCH) * DQK + (kid0 % KCH) * 8, kgo1 = (kid1 / KCH) * DQK + (kid1 % KCH) * 8, kgo2 = (kid2 / KCH) * DQK + (kid2 % KCH) * 8;
;   const int kso0 = (kid0 / KCH) * KROW + (kid0 % KCH) * 8, kso1 = (kid1 / KCH) * KROW + (kid1 % KCH) * 8, kso2 = (kid2 / KCH) * KROW + (kid2 % KCH) * 8;
;   const int vrow0 = tid >> 3, vcc = (tid & 7) * 8;
;   const bf16_t* Vg0 = Vt + (size_t)vrow0 * NKEY + vcc;
;   const bf16_t* Vg1 = Vt + (size_t)(vrow0 + 32) * NKEY + vcc;
;   const int vso0 = vrow0 * VROW + vcc, vso1 = (vrow0 + 32) * VROW + vcc;
;   uint4 pk0, pk1, pk2, pv0, pv1, qk0, qk1, qk2, qv0, qv1;
;   pk2 = make_uint4(0, 0, 0, 0); qk2 = pk2;
;     ...
;   f32x16 o0, o1;
; #pragma unroll
;   for (int i = 0; i < 16; ++i) { o0[i] = 0.f; o1[i] = 0.f; }
;   float m = -1e30f, l = 0.f;
.Lat_ty_1:
	s_mul_i32 s54, s10, 43
	s_lshr_b32 s54, s54, 8
	s_mul_i32 s11, s54, 6
	s_sub_u32 s55, s10, s11
	s_lshl_b32 s11, s54, 12
	s_add_u32 s11, s11, s56
	s_sub_u32 s11, s11, 256
	s_lshl_b32 s28, s57, 5
	s_add_u32 s11, s11, s28
	v_add_u32_e32 v252, s11, v253
	v_lshlrev_b32_e32 v252, 11, v252
	v_lshl_add_u32 v252, v140, 3, v252
	s_cmp_eq_u32 s53, 1
	s_cbranch_scc1 .Lat_mla_2
	s_mul_i32 s11, s54, 6
	s_add_u32 s11, s11, s55
	s_mul_i32 s28, s11, 0x88000
	s_add_u32 s28, s28, 0x7f80000
	s_add_u32 s58, s24, s28
	s_addc_u32 s59, s25, 0
	s_mul_i32 s29, s55, 43
	s_lshr_b32 s29, s29, 7
	s_lshl_b32 s11, s54, 1
	s_add_u32 s11, s11, s29
	s_mul_i32 s28, s11, 0x88000
	s_add_u32 s28, s28, 0x9900000
	s_add_u32 s60, s24, s28
	s_addc_u32 s61, s25, 0
	s_mul_i32 s28, s11, 0x88000
	s_add_u32 s28, s28, 0xa180000
	s_add_u32 s62, s24, s28
	s_addc_u32 s63, s25, 0
	s_lshl_b32 s28, s55, 7
	s_add_u32 s28, s28, 0x200
	v_add_u32_e32 v252, s28, v252
	s_lshl_b32 s28, s57, 5
	s_add_u32 s28, s28, s56
	v_add_u32_e32 v251, s28, v253
	s_movk_i32 s29, 128
	v_mul_lo_u32 v251, v251, s29
	v_lshl_add_u32 v251, v140, 4, v251
	s_movk_i32 s29, 144
	v_mul_lo_u32 v238, v253, s29
	v_lshl_add_u32 v238, v140, 4, v238
	s_movk_i32 s29, 136
	v_mul_lo_u32 v239, v253, s29
	v_lshl_add_u32 v239, v140, 3, v239
	v_add_u32_e32 v240, 0x1100, v239
	v_mov_b32_e32 v225, v143
	v_lshrrev_b32_e32 v226, 3, v225
	v_and_b32_e32 v227, 7, v225
	s_movk_i32 s29, 128
	v_mul_lo_u32 v246, v226, s29
	v_lshl_add_u32 v246, v227, 4, v246
	s_movk_i32 s29, 144
	v_mul_lo_u32 v241, v226, s29
	v_lshl_add_u32 v241, v227, 4, v241
	v_add_u32_e32 v225, 256, v143
	v_lshrrev_b32_e32 v226, 3, v225
	v_and_b32_e32 v227, 7, v225
	s_movk_i32 s29, 128
	v_mul_lo_u32 v247, v226, s29
	v_lshl_add_u32 v247, v227, 4, v247
	s_movk_i32 s29, 144
	v_mul_lo_u32 v242, v226, s29
	v_lshl_add_u32 v242, v227, 4, v242
	v_lshrrev_b32_e32 v226, 3, v143
	v_and_b32_e32 v227, 7, v143
	s_movk_i32 s29, 8704
	v_mul_lo_u32 v249, v226, s29
	v_lshl_add_u32 v249, v227, 4, v249
	v_add_u32_e32 v250, 0x44000, v249
	s_movk_i32 s29, 136
	v_mul_lo_u32 v244, v226, s29
	v_lshl_add_u32 v244, v227, 4, v244
	v_add_u32_e32 v245, 0x1100, v244
	s_barrier
	global_load_dwordx4 v[112:115], v251, s[58:59] offset:0
	global_load_dwordx4 v[116:119], v251, s[58:59] offset:32
	global_load_dwordx4 v[120:123], v251, s[58:59] offset:64
	global_load_dwordx4 v[124:127], v251, s[58:59] offset:96
	s_mov_b32 s1, 0
	s_min_u32 s0, s1, 67
	s_mul_i32 s0, s0, 0x2000
	s_add_u32 s64, s60, s0
	s_addc_u32 s65, s61, 0
	s_min_u32 s0, s1, 67
	s_lshl_b32 s0, s0, 7
	s_add_u32 s66, s62, s0
	s_addc_u32 s67, s63, 0
	global_load_dwordx4 v[176:179], v246, s[64:65]
	global_load_dwordx4 v[180:183], v247, s[64:65]
	global_load_dwordx4 v[212:215], v249, s[66:67]
	global_load_dwordx4 v[216:219], v250, s[66:67]
	s_waitcnt vmcnt(0)
	ds_write_b128 v241, v[176:179] offset:0
	ds_write_b128 v242, v[180:183] offset:0
	ds_write_b64 v244, v[212:213] offset:18432
	ds_write_b64 v244, v[214:215] offset:18440
	ds_write_b64 v245, v[216:217] offset:18432
	ds_write_b64 v245, v[218:219] offset:18440
	s_mov_b32 s1, 1
	s_min_u32 s0, s1, 67
	s_mul_i32 s0, s0, 0x2000
	s_add_u32 s64, s60, s0
	s_addc_u32 s65, s61, 0
	s_min_u32 s0, s1, 67
	s_lshl_b32 s0, s0, 7
	s_add_u32 s66, s62, s0
	s_addc_u32 s67, s63, 0
	global_load_dwordx4 v[176:179], v246, s[64:65]
	global_load_dwordx4 v[180:183], v247, s[64:65]
	s_waitcnt vmcnt(0)
	ds_write_b128 v241, v[176:179] offset:9216
	ds_write_b128 v242, v[180:183] offset:9216
	s_mov_b32 s1, 2
	s_mov_b32 s10, 1
	s_min_u32 s0, s1, 67
	s_mul_i32 s0, s0, 0x2000
	s_add_u32 s64, s60, s0
	s_addc_u32 s65, s61, 0
	s_min_u32 s0, s10, 67
	s_lshl_b32 s0, s0, 7
	s_add_u32 s66, s62, s0
	s_addc_u32 s67, s63, 0
	global_load_dwordx4 v[176:179], v246, s[64:65]
	global_load_dwordx4 v[180:183], v247, s[64:65]
	global_load_dwordx4 v[212:215], v249, s[66:67]
	global_load_dwordx4 v[216:219], v250, s[66:67]
	v_mov_b32_e32 v0, 0
	v_mov_b32_e32 v1, 0
	v_mov_b32_e32 v2, 0
	v_mov_b32_e32 v3, 0
	v_mov_b32_e32 v4, 0
	v_mov_b32_e32 v5, 0
	v_mov_b32_e32 v6, 0
	v_mov_b32_e32 v7, 0
	v_mov_b32_e32 v8, 0
	v_mov_b32_e32 v9, 0
	v_mov_b32_e32 v10, 0
	v_mov_b32_e32 v11, 0
	v_mov_b32_e32 v12, 0
	v_mov_b32_e32 v13, 0
	v_mov_b32_e32 v14, 0
	v_mov_b32_e32 v15, 0
	v_mov_b32_e32 v16, 0
	v_mov_b32_e32 v17, 0
	v_mov_b32_e32 v18, 0
	v_mov_b32_e32 v19, 0
	v_mov_b32_e32 v20, 0
	v_mov_b32_e32 v21, 0
	v_mov_b32_e32 v22, 0
	v_mov_b32_e32 v23, 0
	v_mov_b32_e32 v24, 0
	v_mov_b32_e32 v25, 0
	v_mov_b32_e32 v26, 0
	v_mov_b32_e32 v27, 0
	v_mov_b32_e32 v28, 0
	v_mov_b32_e32 v29, 0
	v_mov_b32_e32 v30, 0
	v_mov_b32_e32 v31, 0
	v_mov_b32_e32 v221, 0
	s_waitcnt lgkmcnt(0)
	s_barrier
	ds_read_b128 v[144:147], v238 offset:0
	ds_read_b128 v[148:151], v238 offset:4608
	ds_read_b128 v[152:155], v238 offset:32
	ds_read_b128 v[156:159], v238 offset:4640
	s_waitcnt lgkmcnt(3)
	v_mfma_f32_32x32x16_bf16 v[32:47], v[144:147], v[112:115], 0
	ds_read_b128 v[144:147], v238 offset:64
	s_waitcnt lgkmcnt(3)
	v_mfma_f32_32x32x16_bf16 v[48:63], v[148:151], v[112:115], 0
	ds_read_b128 v[148:151], v238 offset:4672
	s_waitcnt lgkmcnt(3)
	v_mfma_f32_32x32x16_bf16 v[32:47], v[152:155], v[116:119], v[32:47]
	ds_read_b128 v[152:155], v238 offset:96
	s_waitcnt lgkmcnt(3)
	v_mfma_f32_32x32x16_bf16 v[48:63], v[156:159], v[116:119], v[48:63]
	ds_read_b128 v[156:159], v238 offset:4704
	s_waitcnt lgkmcnt(3)
	v_mfma_f32_32x32x16_bf16 v[32:47], v[144:147], v[120:123], v[32:47]
	s_waitcnt lgkmcnt(2)
	v_mfma_f32_32x32x16_bf16 v[48:63], v[148:151], v[120:123], v[48:63]
	s_waitcnt lgkmcnt(1)
	v_mfma_f32_32x32x16_bf16 v[32:47], v[152:155], v[124:127], v[32:47]
	s_waitcnt lgkmcnt(0)
	v_mfma_f32_32x32x16_bf16 v[48:63], v[156:159], v[124:127], v[48:63]
	s_waitcnt lgkmcnt(0)
	s_barrier
	s_nop 7
	s_nop 3
	v_max3_f32 v223, v32, v33, v34
	v_max3_f32 v224, v40, v41, v42
	v_max3_f32 v225, v48, v49, v50
	v_max3_f32 v226, v56, v57, v58
	v_max3_f32 v223, v223, v35, v36
	v_max3_f32 v224, v224, v43, v44
	v_max3_f32 v225, v225, v51, v52
	v_max3_f32 v226, v226, v59, v60
	v_max3_f32 v223, v223, v37, v38
	v_max3_f32 v224, v224, v45, v46
	v_max3_f32 v225, v225, v53, v54
	v_max3_f32 v226, v226, v61, v62
	v_max_f32_e32 v223, v223, v39
	v_max_f32_e32 v224, v224, v47
	v_max_f32_e32 v225, v225, v55
	v_max_f32_e32 v226, v226, v63
	v_max3_f32 v222, v223, v224, v225
	v_max_f32_e32 v222, v222, v226
	v_mov_b32_e32 v227, v222
	s_nop 1
	v_permlane32_swap_b32_e32 v222, v227
	v_max_f32_e32 v222, v222, v227
	v_sub_f32_e32 v32, v32, v222
	v_sub_f32_e32 v33, v33, v222
	v_sub_f32_e32 v34, v34, v222
	v_sub_f32_e32 v35, v35, v222
	v_sub_f32_e32 v36, v36, v222
	v_sub_f32_e32 v37, v37, v222
	v_sub_f32_e32 v38, v38, v222
	v_sub_f32_e32 v39, v39, v222
	v_sub_f32_e32 v40, v40, v222
	v_sub_f32_e32 v41, v41, v222
	v_sub_f32_e32 v42, v42, v222
	v_sub_f32_e32 v43, v43, v222
	v_sub_f32_e32 v44, v44, v222
	v_sub_f32_e32 v45, v45, v222
	v_sub_f32_e32 v46, v46, v222
	v_sub_f32_e32 v47, v47, v222
	v_sub_f32_e32 v48, v48, v222
	v_sub_f32_e32 v49, v49, v222
	v_sub_f32_e32 v50, v50, v222
	v_sub_f32_e32 v51, v51, v222
	v_sub_f32_e32 v52, v52, v222
	v_sub_f32_e32 v53, v53, v222
	v_sub_f32_e32 v54, v54, v222
	v_sub_f32_e32 v55, v55, v222
	v_sub_f32_e32 v56, v56, v222
	v_sub_f32_e32 v57, v57, v222
	v_sub_f32_e32 v58, v58, v222
	v_sub_f32_e32 v59, v59, v222
	v_sub_f32_e32 v60, v60, v222
	v_sub_f32_e32 v61, v61, v222
	v_sub_f32_e32 v62, v62, v222
	v_sub_f32_e32 v63, v63, v222
	v_sub_f32_e32 v160, 0, v222
	v_sub_f32_e32 v161, 0, v222
	v_sub_f32_e32 v162, 0, v222
	v_sub_f32_e32 v163, 0, v222
	v_sub_f32_e32 v164, 0, v222
	v_sub_f32_e32 v165, 0, v222
	v_sub_f32_e32 v166, 0, v222
	v_sub_f32_e32 v167, 0, v222
	v_sub_f32_e32 v168, 0, v222
	v_sub_f32_e32 v169, 0, v222
	v_sub_f32_e32 v170, 0, v222
	v_sub_f32_e32 v171, 0, v222
	v_sub_f32_e32 v172, 0, v222
	v_sub_f32_e32 v173, 0, v222
	v_sub_f32_e32 v174, 0, v222
	v_sub_f32_e32 v175, 0, v222
	s_mov_b32 s69, 0
	s_mov_b32 s68, 0
.Lat_loop_g:
	s_waitcnt vmcnt(0)
	ds_write_b128 v241, v[176:179] offset:0
	ds_write_b128 v242, v[180:183] offset:0
	ds_write_b64 v244, v[212:213] offset:27136
	ds_write_b64 v244, v[214:215] offset:27144
	ds_write_b64 v245, v[216:217] offset:27136
	ds_write_b64 v245, v[218:219] offset:27144
	s_add_u32 s1, s68, 3
	s_add_u32 s10, s68, 2
	s_min_u32 s0, s1, 67
	s_mul_i32 s0, s0, 0x2000
	s_add_u32 s64, s60, s0
	s_addc_u32 s65, s61, 0
	s_min_u32 s0, s10, 67
	s_lshl_b32 s0, s0, 7
	s_add_u32 s66, s62, s0
	s_addc_u32 s67, s63, 0
	global_load_dwordx4 v[176:179], v246, s[64:65]
	global_load_dwordx4 v[180:183], v247, s[64:65]
	global_load_dwordx4 v[212:215], v249, s[66:67]
	global_load_dwordx4 v[216:219], v250, s[66:67]
	s_cmp_eq_u32 s69, 0
	s_cbranch_scc1 .Lat_nopend_4
	v_sub_f32_e32 v32, v32, v220
	v_sub_f32_e32 v33, v33, v220
	v_sub_f32_e32 v34, v34, v220
	v_sub_f32_e32 v35, v35, v220
	v_sub_f32_e32 v36, v36, v220
	v_sub_f32_e32 v37, v37, v220
	v_sub_f32_e32 v38, v38, v220
	v_sub_f32_e32 v39, v39, v220
	v_sub_f32_e32 v40, v40, v220
	v_sub_f32_e32 v41, v41, v220
	v_sub_f32_e32 v42, v42, v220
	v_sub_f32_e32 v43, v43, v220
	v_sub_f32_e32 v44, v44, v220
	v_sub_f32_e32 v45, v45, v220
	v_sub_f32_e32 v46, v46, v220
	v_sub_f32_e32 v47, v47, v220
	v_sub_f32_e32 v48, v48, v220
	v_sub_f32_e32 v49, v49, v220
	v_sub_f32_e32 v50, v50, v220
	v_sub_f32_e32 v51, v51, v220
	v_sub_f32_e32 v52, v52, v220
	v_sub_f32_e32 v53, v53, v220
	v_sub_f32_e32 v54, v54, v220
	v_sub_f32_e32 v55, v55, v220
	v_sub_f32_e32 v56, v56, v220
	v_sub_f32_e32 v57, v57, v220
	v_sub_f32_e32 v58, v58, v220
	v_sub_f32_e32 v59, v59, v220
	v_sub_f32_e32 v60, v60, v220
	v_sub_f32_e32 v61, v61, v220
	v_sub_f32_e32 v62, v62, v220
	v_sub_f32_e32 v63, v63, v220
	s_mov_b32 s69, 0
.Lat_nopend_4:
	ds_read_b128 v[144:147], v238 offset:9216
	ds_read_b128 v[148:151], v238 offset:13824
	ds_read_b128 v[152:155], v238 offset:9248
	ds_read_b128 v[156:159], v238 offset:13856
	v_max3_f32 v223, v32, v33, v34
	v_max3_f32 v224, v40, v41, v42
	v_max3_f32 v225, v48, v49, v50
	v_max3_f32 v226, v56, v57, v58
	v_max3_f32 v223, v223, v35, v36
	v_max3_f32 v224, v224, v43, v44
	s_waitcnt lgkmcnt(3)
	v_mfma_f32_32x32x16_bf16 v[64:79], v[144:147], v[112:115], v[160:175]
	ds_read_b128 v[144:147], v238 offset:9280
	v_max3_f32 v225, v225, v51, v52
	v_max3_f32 v226, v226, v59, v60
	v_max3_f32 v223, v223, v37, v38
	v_max3_f32 v224, v224, v45, v46
	v_max3_f32 v225, v225, v53, v54
	v_max3_f32 v226, v226, v61, v62
	s_waitcnt lgkmcnt(3)
	v_mfma_f32_32x32x16_bf16 v[80:95], v[148:151], v[112:115], v[160:175]
	ds_read_b128 v[148:151], v238 offset:13888
	v_max_f32_e32 v223, v223, v39
	v_max_f32_e32 v224, v224, v47
	v_max_f32_e32 v225, v225, v55
	v_max_f32_e32 v226, v226, v63
	v_max3_f32 v222, v223, v224, v225
	v_max_f32_e32 v222, v222, v226
	s_waitcnt lgkmcnt(3)
	v_mfma_f32_32x32x16_bf16 v[64:79], v[152:155], v[116:119], v[64:79]
	ds_read_b128 v[152:155], v238 offset:9312
	v_mov_b32_e32 v227, v222
	v_mov_b32_e32 v228, 0x41000000
	s_nop 0
	v_permlane32_swap_b32_e32 v222, v227
	v_max_f32_e32 v222, v222, v227
	v_cmp_gt_f32_e32 vcc, v222, v228
	s_cbranch_vccz .Lat_nors_5
	v_max_f32_e32 v220, 0, v222
	v_sub_f32_e32 v230, 0, v220
	v_exp_f32_e32 v230, v230
	v_sub_f32_e32 v32, v32, v220
	v_sub_f32_e32 v33, v33, v220
	v_sub_f32_e32 v34, v34, v220
	v_sub_f32_e32 v35, v35, v220
	v_sub_f32_e32 v36, v36, v220
	v_sub_f32_e32 v37, v37, v220
	v_sub_f32_e32 v38, v38, v220
	v_sub_f32_e32 v39, v39, v220
	v_sub_f32_e32 v40, v40, v220
	v_sub_f32_e32 v41, v41, v220
	v_sub_f32_e32 v42, v42, v220
	v_sub_f32_e32 v43, v43, v220
	v_sub_f32_e32 v44, v44, v220
	v_sub_f32_e32 v45, v45, v220
	v_sub_f32_e32 v46, v46, v220
	v_sub_f32_e32 v47, v47, v220
	v_sub_f32_e32 v48, v48, v220
	v_sub_f32_e32 v49, v49, v220
	v_sub_f32_e32 v50, v50, v220
	v_sub_f32_e32 v51, v51, v220
	v_sub_f32_e32 v52, v52, v220
	v_sub_f32_e32 v53, v53, v220
	v_sub_f32_e32 v54, v54, v220
	v_sub_f32_e32 v55, v55, v220
	v_sub_f32_e32 v56, v56, v220
	v_sub_f32_e32 v57, v57, v220
	v_sub_f32_e32 v58, v58, v220
	v_sub_f32_e32 v59, v59, v220
	v_sub_f32_e32 v60, v60, v220
	v_sub_f32_e32 v61, v61, v220
	v_sub_f32_e32 v62, v62, v220
	v_sub_f32_e32 v63, v63, v220
	v_sub_f32_e32 v160, v160, v220
	v_sub_f32_e32 v161, v161, v220
	v_sub_f32_e32 v162, v162, v220
	v_sub_f32_e32 v163, v163, v220
	v_sub_f32_e32 v164, v164, v220
	v_sub_f32_e32 v165, v165, v220
	v_sub_f32_e32 v166, v166, v220
	v_sub_f32_e32 v167, v167, v220
	v_sub_f32_e32 v168, v168, v220
	v_sub_f32_e32 v169, v169, v220
	v_sub_f32_e32 v170, v170, v220
	v_sub_f32_e32 v171, v171, v220
	v_sub_f32_e32 v172, v172, v220
	v_sub_f32_e32 v173, v173, v220
	v_sub_f32_e32 v174, v174, v220
	v_sub_f32_e32 v175, v175, v220
	v_mul_f32_e32 v221, v221, v230
	v_mul_f32_e32 v0, v0, v230
	v_mul_f32_e32 v1, v1, v230
	v_mul_f32_e32 v2, v2, v230
	v_mul_f32_e32 v3, v3, v230
	v_mul_f32_e32 v4, v4, v230
	v_mul_f32_e32 v5, v5, v230
	v_mul_f32_e32 v6, v6, v230
	v_mul_f32_e32 v7, v7, v230
	v_mul_f32_e32 v8, v8, v230
	v_mul_f32_e32 v9, v9, v230
	v_mul_f32_e32 v10, v10, v230
	v_mul_f32_e32 v11, v11, v230
	v_mul_f32_e32 v12, v12, v230
	v_mul_f32_e32 v13, v13, v230
	v_mul_f32_e32 v14, v14, v230
	v_mul_f32_e32 v15, v15, v230
	v_mul_f32_e32 v16, v16, v230
	v_mul_f32_e32 v17, v17, v230
	v_mul_f32_e32 v18, v18, v230
	v_mul_f32_e32 v19, v19, v230
	v_mul_f32_e32 v20, v20, v230
	v_mul_f32_e32 v21, v21, v230
	v_mul_f32_e32 v22, v22, v230
	v_mul_f32_e32 v23, v23, v230
	v_mul_f32_e32 v24, v24, v230
	v_mul_f32_e32 v25, v25, v230
	v_mul_f32_e32 v26, v26, v230
	v_mul_f32_e32 v27, v27, v230
	v_mul_f32_e32 v28, v28, v230
	v_mul_f32_e32 v29, v29, v230
	v_mul_f32_e32 v30, v30, v230
	v_mul_f32_e32 v31, v31, v230
	s_mov_b32 s69, 1
.Lat_nors_5:
	s_waitcnt lgkmcnt(3)
	v_mfma_f32_32x32x16_bf16 v[80:95], v[156:159], v[116:119], v[80:95]
	ds_read_b128 v[156:159], v238 offset:13920
	v_exp_f32_e32 v32, v32
	v_exp_f32_e32 v33, v33
	v_exp_f32_e32 v34, v34
	v_exp_f32_e32 v35, v35
	v_exp_f32_e32 v36, v36
	v_exp_f32_e32 v37, v37
	s_waitcnt lgkmcnt(3)
	v_mfma_f32_32x32x16_bf16 v[64:79], v[144:147], v[120:123], v[64:79]
	v_exp_f32_e32 v38, v38
	v_exp_f32_e32 v39, v39
	v_exp_f32_e32 v40, v40
	v_exp_f32_e32 v41, v41
	v_exp_f32_e32 v42, v42
	v_exp_f32_e32 v43, v43
	s_waitcnt lgkmcnt(2)
	v_mfma_f32_32x32x16_bf16 v[80:95], v[148:151], v[120:123], v[80:95]
	v_exp_f32_e32 v44, v44
	v_exp_f32_e32 v45, v45
	v_exp_f32_e32 v46, v46
	v_exp_f32_e32 v47, v47
	v_exp_f32_e32 v48, v48
	v_exp_f32_e32 v49, v49
	s_waitcnt lgkmcnt(1)
	v_mfma_f32_32x32x16_bf16 v[64:79], v[152:155], v[124:127], v[64:79]
	v_exp_f32_e32 v50, v50
	v_exp_f32_e32 v51, v51
	v_exp_f32_e32 v52, v52
	v_exp_f32_e32 v53, v53
	v_exp_f32_e32 v54, v54
	v_exp_f32_e32 v55, v55
	s_waitcnt lgkmcnt(0)
	v_mfma_f32_32x32x16_bf16 v[80:95], v[156:159], v[124:127], v[80:95]
	v_exp_f32_e32 v56, v56
	v_exp_f32_e32 v57, v57
	v_exp_f32_e32 v58, v58
	v_exp_f32_e32 v59, v59
	v_exp_f32_e32 v60, v60
	v_exp_f32_e32 v61, v61
	v_exp_f32_e32 v62, v62
	v_exp_f32_e32 v63, v63
	v_add_u32_e32 v223, 0x4800, v239
	v_add_u32_e32 v224, 0x4800, v240
	ds_read2_b64 v[144:147], v223 offset0:0 offset1:2
	ds_read2_b64 v[148:151], v224 offset0:0 offset1:2
	ds_read2_b64 v[152:155], v223 offset0:4 offset1:6
	ds_read2_b64 v[156:159], v224 offset0:4 offset1:6
	v_cvt_pk_bf16_f32 v96, v32, v33
	v_cvt_pk_bf16_f32 v97, v34, v35
	v_cvt_pk_bf16_f32 v98, v36, v37
	v_cvt_pk_bf16_f32 v99, v38, v39
	v_add_f32_e32 v231, v32, v36
	v_add_f32_e32 v232, v33, v37
	v_add_f32_e32 v233, v34, v38
	v_add_f32_e32 v237, v35, v39
	s_waitcnt lgkmcnt(3)
	v_mfma_f32_32x32x16_bf16 v[0:15], v[144:147], v[96:99], v[0:15]
	ds_read2_b64 v[144:147], v223 offset0:8 offset1:10
	s_waitcnt lgkmcnt(3)
	v_mfma_f32_32x32x16_bf16 v[16:31], v[148:151], v[96:99], v[16:31]
	ds_read2_b64 v[148:151], v224 offset0:8 offset1:10
	v_cvt_pk_bf16_f32 v100, v40, v41
	v_cvt_pk_bf16_f32 v101, v42, v43
	v_cvt_pk_bf16_f32 v102, v44, v45
	v_cvt_pk_bf16_f32 v103, v46, v47
	v_add_f32_e32 v231, v231, v40
	v_add_f32_e32 v232, v232, v41
	v_add_f32_e32 v233, v233, v42
	v_add_f32_e32 v237, v237, v43
	v_add_f32_e32 v231, v231, v44
	v_add_f32_e32 v232, v232, v45
	v_add_f32_e32 v233, v233, v46
	v_add_f32_e32 v237, v237, v47
	s_waitcnt lgkmcnt(3)
	v_mfma_f32_32x32x16_bf16 v[0:15], v[152:155], v[100:103], v[0:15]
	ds_read2_b64 v[152:155], v223 offset0:12 offset1:14
	s_waitcnt lgkmcnt(3)
	v_mfma_f32_32x32x16_bf16 v[16:31], v[156:159], v[100:103], v[16:31]
	ds_read2_b64 v[156:159], v224 offset0:12 offset1:14
	v_cvt_pk_bf16_f32 v104, v48, v49
	v_cvt_pk_bf16_f32 v105, v50, v51
	v_cvt_pk_bf16_f32 v106, v52, v53
	v_cvt_pk_bf16_f32 v107, v54, v55
	v_add_f32_e32 v231, v231, v48
	v_add_f32_e32 v232, v232, v49
	v_add_f32_e32 v233, v233, v50
	v_add_f32_e32 v237, v237, v51
	v_add_f32_e32 v231, v231, v52
	v_add_f32_e32 v232, v232, v53
	v_add_f32_e32 v233, v233, v54
	v_add_f32_e32 v237, v237, v55
	s_waitcnt lgkmcnt(3)
	v_mfma_f32_32x32x16_bf16 v[0:15], v[144:147], v[104:107], v[0:15]
	s_waitcnt lgkmcnt(2)
	v_mfma_f32_32x32x16_bf16 v[16:31], v[148:151], v[104:107], v[16:31]
	v_cvt_pk_bf16_f32 v108, v56, v57
	v_cvt_pk_bf16_f32 v109, v58, v59
	v_cvt_pk_bf16_f32 v110, v60, v61
	v_cvt_pk_bf16_f32 v111, v62, v63
	v_add_f32_e32 v231, v231, v56
	v_add_f32_e32 v232, v232, v57
	v_add_f32_e32 v233, v233, v58
	v_add_f32_e32 v237, v237, v59
	v_add_f32_e32 v231, v231, v60
	v_add_f32_e32 v232, v232, v61
	v_add_f32_e32 v233, v233, v62
	v_add_f32_e32 v237, v237, v63
	s_waitcnt lgkmcnt(1)
	v_mfma_f32_32x32x16_bf16 v[0:15], v[152:155], v[108:111], v[0:15]
	s_waitcnt lgkmcnt(0)
	v_mfma_f32_32x32x16_bf16 v[16:31], v[156:159], v[108:111], v[16:31]
	v_add_f32_e32 v231, v231, v232
	v_add_f32_e32 v233, v233, v237
	v_add_f32_e32 v231, v231, v233
	v_add_f32_e32 v221, v221, v231
	s_add_u32 s68, s68, 1
	s_waitcnt lgkmcnt(0)
	s_barrier
; template <int DQK>
; DI void attn_item(const bf16_t* __restrict__ Q, const bf16_t* __restrict__ Kp, const bf16_t* __restrict__ Vt, int q0, int nkeys,
;                   bf16_t* __restrict__ mix, int colbase, int b, char* smem) {
;     ...
;   for (int kt = 0; kt < nt; kt += 2) {
;     A_TILE(0)
;     A_WRITE(q, 1)
;     __syncthreads();
;     if (kt + 3 < nt) A_LOAD(q, (kt + 3) << 6)
;     A_TILE(1)
;     if (kt + 2 < nt) A_WRITE(p, 0)
;     __syncthreads();
;     if (kt + 4 < nt) A_LOAD(p, (kt + 4) << 6)
	s_waitcnt vmcnt(0)
	ds_write_b128 v241, v[176:179] offset:9216
	ds_write_b128 v242, v[180:183] offset:9216
	ds_write_b64 v244, v[212:213] offset:18432
	ds_write_b64 v244, v[214:215] offset:18440
	ds_write_b64 v245, v[216:217] offset:18432
	ds_write_b64 v245, v[218:219] offset:18440
	s_add_u32 s1, s68, 3
	s_add_u32 s10, s68, 2
	s_min_u32 s0, s1, 67
	s_mul_i32 s0, s0, 0x2000
	s_add_u32 s64, s60, s0
	s_addc_u32 s65, s61, 0
	s_min_u32 s0, s10, 67
	s_lshl_b32 s0, s0, 7
	s_add_u32 s66, s62, s0
	s_addc_u32 s67, s63, 0
	global_load_dwordx4 v[176:179], v246, s[64:65]
	global_load_dwordx4 v[180:183], v247, s[64:65]
	global_load_dwordx4 v[212:215], v249, s[66:67]
	global_load_dwordx4 v[216:219], v250, s[66:67]
	s_cmp_eq_u32 s69, 0
	s_cbranch_scc1 .Lat_nopend_6
	v_sub_f32_e32 v64, v64, v220
	v_sub_f32_e32 v65, v65, v220
	v_sub_f32_e32 v66, v66, v220
	v_sub_f32_e32 v67, v67, v220
	v_sub_f32_e32 v68, v68, v220
	v_sub_f32_e32 v69, v69, v220
	v_sub_f32_e32 v70, v70, v220
	v_sub_f32_e32 v71, v71, v220
	v_sub_f32_e32 v72, v72, v220
	v_sub_f32_e32 v73, v73, v220
	v_sub_f32_e32 v74, v74, v220
	v_sub_f32_e32 v75, v75, v220
	v_sub_f32_e32 v76, v76, v220
	v_sub_f32_e32 v77, v77, v220
	v_sub_f32_e32 v78, v78, v220
	v_sub_f32_e32 v79, v79, v220
	v_sub_f32_e32 v80, v80, v220
	v_sub_f32_e32 v81, v81, v220
	v_sub_f32_e32 v82, v82, v220
	v_sub_f32_e32 v83, v83, v220
	v_sub_f32_e32 v84, v84, v220
	v_sub_f32_e32 v85, v85, v220
	v_sub_f32_e32 v86, v86, v220
	v_sub_f32_e32 v87, v87, v220
	v_sub_f32_e32 v88, v88, v220
	v_sub_f32_e32 v89, v89, v220
	v_sub_f32_e32 v90, v90, v220
	v_sub_f32_e32 v91, v91, v220
	v_sub_f32_e32 v92, v92, v220
	v_sub_f32_e32 v93, v93, v220
	v_sub_f32_e32 v94, v94, v220
	v_sub_f32_e32 v95, v95, v220
	s_mov_b32 s69, 0
.Lat_nopend_6:
	ds_read_b128 v[144:147], v238 offset:0
	ds_read_b128 v[148:151], v238 offset:4608
	ds_read_b128 v[152:155], v238 offset:32
	ds_read_b128 v[156:159], v238 offset:4640
	v_max3_f32 v223, v64, v65, v66
	v_max3_f32 v224, v72, v73, v74
	v_max3_f32 v225, v80, v81, v82
	v_max3_f32 v226, v88, v89, v90
	v_max3_f32 v223, v223, v67, v68
	v_max3_f32 v224, v224, v75, v76
	s_waitcnt lgkmcnt(3)
	v_mfma_f32_32x32x16_bf16 v[32:47], v[144:147], v[112:115], v[160:175]
	ds_read_b128 v[144:147], v238 offset:64
	v_max3_f32 v225, v225, v83, v84
	v_max3_f32 v226, v226, v91, v92
	v_max3_f32 v223, v223, v69, v70
	v_max3_f32 v224, v224, v77, v78
	v_max3_f32 v225, v225, v85, v86
	v_max3_f32 v226, v226, v93, v94
	s_waitcnt lgkmcnt(3)
	v_mfma_f32_32x32x16_bf16 v[48:63], v[148:151], v[112:115], v[160:175]
	ds_read_b128 v[148:151], v238 offset:4672
	v_max_f32_e32 v223, v223, v71
	v_max_f32_e32 v224, v224, v79
	v_max_f32_e32 v225, v225, v87
	v_max_f32_e32 v226, v226, v95
	v_max3_f32 v222, v223, v224, v225
	v_max_f32_e32 v222, v222, v226
	s_waitcnt lgkmcnt(3)
	v_mfma_f32_32x32x16_bf16 v[32:47], v[152:155], v[116:119], v[32:47]
	ds_read_b128 v[152:155], v238 offset:96
	v_mov_b32_e32 v227, v222
	v_mov_b32_e32 v228, 0x41000000
	s_nop 0
	v_permlane32_swap_b32_e32 v222, v227
	v_max_f32_e32 v222, v222, v227
	v_cmp_gt_f32_e32 vcc, v222, v228
	s_cbranch_vccz .Lat_nors_7
	v_max_f32_e32 v220, 0, v222
	v_sub_f32_e32 v230, 0, v220
	v_exp_f32_e32 v230, v230
	v_sub_f32_e32 v64, v64, v220
	v_sub_f32_e32 v65, v65, v220
	v_sub_f32_e32 v66, v66, v220
	v_sub_f32_e32 v67, v67, v220
	v_sub_f32_e32 v68, v68, v220
	v_sub_f32_e32 v69, v69, v220
	v_sub_f32_e32 v70, v70, v220
	v_sub_f32_e32 v71, v71, v220
	v_sub_f32_e32 v72, v72, v220
	v_sub_f32_e32 v73, v73, v220
	v_sub_f32_e32 v74, v74, v220
	v_sub_f32_e32 v75, v75, v220
	v_sub_f32_e32 v76, v76, v220
	v_sub_f32_e32 v77, v77, v220
	v_sub_f32_e32 v78, v78, v220
	v_sub_f32_e32 v79, v79, v220
	v_sub_f32_e32 v80, v80, v220
	v_sub_f32_e32 v81, v81, v220
	v_sub_f32_e32 v82, v82, v220
	v_sub_f32_e32 v83, v83, v220
	v_sub_f32_e32 v84, v84, v220
	v_sub_f32_e32 v85, v85, v220
	v_sub_f32_e32 v86, v86, v220
	v_sub_f32_e32 v87, v87, v220
	v_sub_f32_e32 v88, v88, v220
	v_sub_f32_e32 v89, v89, v220
	v_sub_f32_e32 v90, v90, v220
	v_sub_f32_e32 v91, v91, v220
	v_sub_f32_e32 v92, v92, v220
	v_sub_f32_e32 v93, v93, v220
	v_sub_f32_e32 v94, v94, v220
	v_sub_f32_e32 v95, v95, v220
	v_sub_f32_e32 v160, v160, v220
	v_sub_f32_e32 v161, v161, v220
	v_sub_f32_e32 v162, v162, v220
	v_sub_f32_e32 v163, v163, v220
	v_sub_f32_e32 v164, v164, v220
	v_sub_f32_e32 v165, v165, v220
	v_sub_f32_e32 v166, v166, v220
	v_sub_f32_e32 v167, v167, v220
	v_sub_f32_e32 v168, v168, v220
	v_sub_f32_e32 v169, v169, v220
	v_sub_f32_e32 v170, v170, v220
	v_sub_f32_e32 v171, v171, v220
	v_sub_f32_e32 v172, v172, v220
	v_sub_f32_e32 v173, v173, v220
	v_sub_f32_e32 v174, v174, v220
	v_sub_f32_e32 v175, v175, v220
	v_mul_f32_e32 v221, v221, v230
	v_mul_f32_e32 v0, v0, v230
	v_mul_f32_e32 v1, v1, v230
	v_mul_f32_e32 v2, v2, v230
	v_mul_f32_e32 v3, v3, v230
	v_mul_f32_e32 v4, v4, v230
	v_mul_f32_e32 v5, v5, v230
	v_mul_f32_e32 v6, v6, v230
	v_mul_f32_e32 v7, v7, v230
	v_mul_f32_e32 v8, v8, v230
	v_mul_f32_e32 v9, v9, v230
	v_mul_f32_e32 v10, v10, v230
	v_mul_f32_e32 v11, v11, v230
	v_mul_f32_e32 v12, v12, v230
	v_mul_f32_e32 v13, v13, v230
	v_mul_f32_e32 v14, v14, v230
	v_mul_f32_e32 v15, v15, v230
	v_mul_f32_e32 v16, v16, v230
	v_mul_f32_e32 v17, v17, v230
	v_mul_f32_e32 v18, v18, v230
	v_mul_f32_e32 v19, v19, v230
	v_mul_f32_e32 v20, v20, v230
	v_mul_f32_e32 v21, v21, v230
	v_mul_f32_e32 v22, v22, v230
	v_mul_f32_e32 v23, v23, v230
	v_mul_f32_e32 v24, v24, v230
	v_mul_f32_e32 v25, v25, v230
	v_mul_f32_e32 v26, v26, v230
	v_mul_f32_e32 v27, v27, v230
	v_mul_f32_e32 v28, v28, v230
	v_mul_f32_e32 v29, v29, v230
	v_mul_f32_e32 v30, v30, v230
	v_mul_f32_e32 v31, v31, v230
	s_mov_b32 s69, 1
; DI unsigned pack2(float lo, float hi) { f32x2_t v = {lo, hi}; bf16x2_t r = __builtin_convertvector(v, bf16x2_t); return __builtin_bit_cast(unsigned, r); }
; DI float xhalf_sum(float x) { auto r = __builtin_amdgcn_permlane32_swap(__float_as_uint(x), __float_as_uint(x), false, false); return __uint_as_float(r[0]) + __uint_as_float(r[1]); }
; template <int DQK>
; DI void attn_item(const bf16_t* __restrict__ Q, const bf16_t* __restrict__ Kp, const bf16_t* __restrict__ Vt, int q0, int nkeys,
;                   bf16_t* __restrict__ mix, int colbase, int b, char* smem) {
;     ...
;   l = xhalf_sum(l);
;   const float inv = 1.0f / l;
;   const int kp = q0 + wave * 32 + r;
;   bf16_t* orow = mix + (size_t)row_of(b, kp) * D + colbase;
; #pragma unroll
;   for (int g = 0; g < 4; ++g) {
;     uint2 w0, w1;
;     w0.x = pack2(o0[4 * g] * inv, o0[4 * g + 1] * inv); w0.y = pack2(o0[4 * g + 2] * inv, o0[4 * g + 3] * inv);
;     w1.x = pack2(o1[4 * g] * inv, o1[4 * g + 1] * inv); w1.y = pack2(o1[4 * g + 2] * inv, o1[4 * g + 3] * inv);
;     *(uint2*)(orow + 8 * g + 4 * h) = w0;
;     *(uint2*)(orow + 32 + 8 * g + 4 * h) = w1;
;   }
.Lat_nors_7:
	s_waitcnt lgkmcnt(3)
	v_mfma_f32_32x32x16_bf16 v[48:63], v[156:159], v[116:119], v[48:63]
	ds_read_b128 v[156:159], v238 offset:4704
	v_exp_f32_e32 v64, v64
	v_exp_f32_e32 v65, v65
	v_exp_f32_e32 v66, v66
	v_exp_f32_e32 v67, v67
	v_exp_f32_e32 v68, v68
	v_exp_f32_e32 v69, v69
	s_waitcnt lgkmcnt(3)
	v_mfma_f32_32x32x16_bf16 v[32:47], v[144:147], v[120:123], v[32:47]
	v_exp_f32_e32 v70, v70
	v_exp_f32_e32 v71, v71
	v_exp_f32_e32 v72, v72
	v_exp_f32_e32 v73, v73
	v_exp_f32_e32 v74, v74
	v_exp_f32_e32 v75, v75
	s_waitcnt lgkmcnt(2)
	v_mfma_f32_32x32x16_bf16 v[48:63], v[148:151], v[120:123], v[48:63]
	v_exp_f32_e32 v76, v76
	v_exp_f32_e32 v77, v77
	v_exp_f32_e32 v78, v78
	v_exp_f32_e32 v79, v79
	v_exp_f32_e32 v80, v80
	v_exp_f32_e32 v81, v81
	s_waitcnt lgkmcnt(1)
	v_mfma_f32_32x32x16_bf16 v[32:47], v[152:155], v[124:127], v[32:47]
	v_exp_f32_e32 v82, v82
	v_exp_f32_e32 v83, v83
	v_exp_f32_e32 v84, v84
	v_exp_f32_e32 v85, v85
	v_exp_f32_e32 v86, v86
	v_exp_f32_e32 v87, v87
	s_waitcnt lgkmcnt(0)
	v_mfma_f32_32x32x16_bf16 v[48:63], v[156:159], v[124:127], v[48:63]
	v_exp_f32_e32 v88, v88
	v_exp_f32_e32 v89, v89
	v_exp_f32_e32 v90, v90
	v_exp_f32_e32 v91, v91
	v_exp_f32_e32 v92, v92
	v_exp_f32_e32 v93, v93
	v_exp_f32_e32 v94, v94
	v_exp_f32_e32 v95, v95
	v_add_u32_e32 v223, 0x6a00, v239
	v_add_u32_e32 v224, 0x6a00, v240
	ds_read2_b64 v[144:147], v223 offset0:0 offset1:2
	ds_read2_b64 v[148:151], v224 offset0:0 offset1:2
	ds_read2_b64 v[152:155], v223 offset0:4 offset1:6
	ds_read2_b64 v[156:159], v224 offset0:4 offset1:6
	v_cvt_pk_bf16_f32 v96, v64, v65
	v_cvt_pk_bf16_f32 v97, v66, v67
	v_cvt_pk_bf16_f32 v98, v68, v69
	v_cvt_pk_bf16_f32 v99, v70, v71
	v_add_f32_e32 v231, v64, v68
	v_add_f32_e32 v232, v65, v69
	v_add_f32_e32 v233, v66, v70
	v_add_f32_e32 v237, v67, v71
	s_waitcnt lgkmcnt(3)
	v_mfma_f32_32x32x16_bf16 v[0:15], v[144:147], v[96:99], v[0:15]
	ds_read2_b64 v[144:147], v223 offset0:8 offset1:10
	s_waitcnt lgkmcnt(3)
	v_mfma_f32_32x32x16_bf16 v[16:31], v[148:151], v[96:99], v[16:31]
	ds_read2_b64 v[148:151], v224 offset0:8 offset1:10
	v_cvt_pk_bf16_f32 v100, v72, v73
	v_cvt_pk_bf16_f32 v101, v74, v75
	v_cvt_pk_bf16_f32 v102, v76, v77
	v_cvt_pk_bf16_f32 v103, v78, v79
	v_add_f32_e32 v231, v231, v72
	v_add_f32_e32 v232, v232, v73
	v_add_f32_e32 v233, v233, v74
	v_add_f32_e32 v237, v237, v75
	v_add_f32_e32 v231, v231, v76
	v_add_f32_e32 v232, v232, v77
	v_add_f32_e32 v233, v233, v78
	v_add_f32_e32 v237, v237, v79
	s_waitcnt lgkmcnt(3)
	v_mfma_f32_32x32x16_bf16 v[0:15], v[152:155], v[100:103], v[0:15]
	ds_read2_b64 v[152:155], v223 offset0:12 offset1:14
	s_waitcnt lgkmcnt(3)
	v_mfma_f32_32x32x16_bf16 v[16:31], v[156:159], v[100:103], v[16:31]
	ds_read2_b64 v[156:159], v224 offset0:12 offset1:14
	v_cvt_pk_bf16_f32 v104, v80, v81
	v_cvt_pk_bf16_f32 v105, v82, v83
	v_cvt_pk_bf16_f32 v106, v84, v85
	v_cvt_pk_bf16_f32 v107, v86, v87
	v_add_f32_e32 v231, v231, v80
	v_add_f32_e32 v232, v232, v81
	v_add_f32_e32 v233, v233, v82
	v_add_f32_e32 v237, v237, v83
	v_add_f32_e32 v231, v231, v84
	v_add_f32_e32 v232, v232, v85
	v_add_f32_e32 v233, v233, v86
	v_add_f32_e32 v237, v237, v87
	s_waitcnt lgkmcnt(3)
	v_mfma_f32_32x32x16_bf16 v[0:15], v[144:147], v[104:107], v[0:15]
	s_waitcnt lgkmcnt(2)
	v_mfma_f32_32x32x16_bf16 v[16:31], v[148:151], v[104:107], v[16:31]
	v_cvt_pk_bf16_f32 v108, v88, v89
	v_cvt_pk_bf16_f32 v109, v90, v91
	v_cvt_pk_bf16_f32 v110, v92, v93
	v_cvt_pk_bf16_f32 v111, v94, v95
	v_add_f32_e32 v231, v231, v88
	v_add_f32_e32 v232, v232, v89
	v_add_f32_e32 v233, v233, v90
	v_add_f32_e32 v237, v237, v91
	v_add_f32_e32 v231, v231, v92
	v_add_f32_e32 v232, v232, v93
	v_add_f32_e32 v233, v233, v94
	v_add_f32_e32 v237, v237, v95
	s_waitcnt lgkmcnt(1)
	v_mfma_f32_32x32x16_bf16 v[0:15], v[152:155], v[108:111], v[0:15]
	s_waitcnt lgkmcnt(0)
	v_mfma_f32_32x32x16_bf16 v[16:31], v[156:159], v[108:111], v[16:31]
	v_add_f32_e32 v231, v231, v232
	v_add_f32_e32 v233, v233, v237
	v_add_f32_e32 v231, v231, v233
	v_add_f32_e32 v221, v221, v231
	s_add_u32 s68, s68, 1
	s_waitcnt lgkmcnt(0)
	s_barrier
	s_cmp_lt_u32 s68, 68
	s_cbranch_scc1 .Lat_loop_g
	s_nop 7
	v_mov_b32_e32 v223, v221
	s_nop 1
	v_permlane32_swap_b32_e32 v221, v223
	v_add_f32_e32 v221, v221, v223
	v_rcp_f32_e32 v224, v221
	s_nop 0
	v_mul_f32_e32 v96, v0, v224
	v_mul_f32_e32 v97, v1, v224
	v_mul_f32_e32 v98, v2, v224
	v_mul_f32_e32 v99, v3, v224
	v_cvt_pk_bf16_f32 v144, v96, v97
	v_cvt_pk_bf16_f32 v145, v98, v99
	global_store_dwordx2 v252, v[144:145], s[72:73] offset:0
	v_mul_f32_e32 v96, v16, v224
	v_mul_f32_e32 v97, v17, v224
	v_mul_f32_e32 v98, v18, v224
	v_mul_f32_e32 v99, v19, v224
	v_cvt_pk_bf16_f32 v146, v96, v97
	v_cvt_pk_bf16_f32 v147, v98, v99
	global_store_dwordx2 v252, v[146:147], s[72:73] offset:64
	v_mul_f32_e32 v96, v4, v224
	v_mul_f32_e32 v97, v5, v224
	v_mul_f32_e32 v98, v6, v224
	v_mul_f32_e32 v99, v7, v224
	v_cvt_pk_bf16_f32 v148, v96, v97
	v_cvt_pk_bf16_f32 v149, v98, v99
	global_store_dwordx2 v252, v[148:149], s[72:73] offset:16
	v_mul_f32_e32 v96, v20, v224
	v_mul_f32_e32 v97, v21, v224
	v_mul_f32_e32 v98, v22, v224
	v_mul_f32_e32 v99, v23, v224
	v_cvt_pk_bf16_f32 v150, v96, v97
	v_cvt_pk_bf16_f32 v151, v98, v99
	global_store_dwordx2 v252, v[150:151], s[72:73] offset:80
	v_mul_f32_e32 v96, v8, v224
	v_mul_f32_e32 v97, v9, v224
	v_mul_f32_e32 v98, v10, v224
	v_mul_f32_e32 v99, v11, v224
	v_cvt_pk_bf16_f32 v152, v96, v97
	v_cvt_pk_bf16_f32 v153, v98, v99
	global_store_dwordx2 v252, v[152:153], s[72:73] offset:32
	v_mul_f32_e32 v96, v24, v224
	v_mul_f32_e32 v97, v25, v224
	v_mul_f32_e32 v98, v26, v224
	v_mul_f32_e32 v99, v27, v224
	v_cvt_pk_bf16_f32 v154, v96, v97
	v_cvt_pk_bf16_f32 v155, v98, v99
	global_store_dwordx2 v252, v[154:155], s[72:73] offset:96
	v_mul_f32_e32 v96, v12, v224
	v_mul_f32_e32 v97, v13, v224
	v_mul_f32_e32 v98, v14, v224
	v_mul_f32_e32 v99, v15, v224
	v_cvt_pk_bf16_f32 v156, v96, v97
	v_cvt_pk_bf16_f32 v157, v98, v99
	global_store_dwordx2 v252, v[156:157], s[72:73] offset:48
	v_mul_f32_e32 v96, v28, v224
	v_mul_f32_e32 v97, v29, v224
	v_mul_f32_e32 v98, v30, v224
	v_mul_f32_e32 v99, v31, v224
	v_cvt_pk_bf16_f32 v158, v96, v97
	v_cvt_pk_bf16_f32 v159, v98, v99
	global_store_dwordx2 v252, v[158:159], s[72:73] offset:112
	s_branch .Lat_tyj_3
; template <int DQK>
; DI void attn_item(const bf16_t* __restrict__ Q, const bf16_t* __restrict__ Kp, const bf16_t* __restrict__ Vt, int q0, int nkeys,
;                   bf16_t* __restrict__ mix, int colbase, int b, char* smem) {
;     ...
;   bf16x8 qf[NSTEP];
;   {
;     const bf16_t* qr = Q + (size_t)(q0 + wave * 32 + r) * DQK + 8 * h;
; #pragma unroll
;     for (int s = 0; s < NSTEP; ++s) qf[s] = *(const bf16x8*)(qr + 16 * s);
;   }
;   const int kid0 = tid, kid1 = tid + 256, kid2 = tid + 512;
;   const int kgo0 = (kid0 / KCH) * DQK + (kid0 % KCH) * 8, kgo1 = (kid1 / KCH) * DQK + (kid1 % KCH) * 8, kgo2 = (kid2 / KCH) * DQK + (kid2 % KCH) * 8;
;   const int kso0 = (kid0 / KCH) * KROW + (kid0 % KCH) * 8, kso1 = (kid1 / KCH) * KROW + (kid1 % KCH) * 8, kso2 = (kid2 / KCH) * KROW + (kid2 % KCH) * 8;
;   const int vrow0 = tid >> 3, vcc = (tid & 7) * 8;
;   const bf16_t* Vg0 = Vt + (size_t)vrow0 * NKEY + vcc;
;   const bf16_t* Vg1 = Vt + (size_t)(vrow0 + 32) * NKEY + vcc;
;   const int vso0 = vrow0 * VROW + vcc, vso1 = (vrow0 + 32) * VROW + vcc;
;   uint4 pk0, pk1, pk2, pv0, pv1, qk0, qk1, qk2, qv0, qv1;
;   pk2 = make_uint4(0, 0, 0, 0); qk2 = pk2;
;     ...
;   f32x16 o0, o1;
; #pragma unroll
;   for (int i = 0; i < 16; ++i) { o0[i] = 0.f; o1[i] = 0.f; }
;   float m = -1e30f, l = 0.f;
; DI void attn_dispatch(const Params& p, int type, int b, int hd, int qb, char* smem) {
;     ...
;     const bf16_t* Q = (const bf16_t*)(p.ws + OFF_QM) + (size_t)(b * 6 + hd) * NKEY * 96;
;     const bf16_t* K = (const bf16_t*)(p.ws + OFF_KM) + (size_t)(b * 6 + hd) * NKEY * 96;
;     const bf16_t* V = (const bf16_t*)(p.ws + OFF_VMT) + (size_t)(b * 6 + hd) * 64 * NKEY;
;     attn_item<96>(Q, K, V, qb * 128, nkeys, MIX, 640 + hd * 64, b, smem);
.Lat_mla_2:
	s_mul_i32 s11, s54, 6
	s_add_u32 s11, s11, s55
	s_mul_i32 s28, s11, 0xcc000
	s_add_u32 s28, s28, 0xaa00000
	s_add_u32 s58, s24, s28
	s_addc_u32 s59, s25, 0
	s_mul_i32 s28, s11, 0xcc000
	s_add_u32 s28, s28, 0xd040000
	s_add_u32 s60, s24, s28
	s_addc_u32 s61, s25, 0
	s_mul_i32 s28, s11, 0x88000
	s_add_u32 s28, s28, 0xf680000
	s_add_u32 s62, s24, s28
	s_addc_u32 s63, s25, 0
	s_lshl_b32 s28, s55, 7
	s_add_u32 s28, s28, 0x500
	v_add_u32_e32 v252, s28, v252
	s_lshl_b32 s28, s57, 5
	s_add_u32 s28, s28, s56
	v_add_u32_e32 v251, s28, v253
	s_movk_i32 s29, 192
	v_mul_lo_u32 v251, v251, s29
	v_lshl_add_u32 v251, v140, 4, v251
	s_movk_i32 s29, 208
	v_mul_lo_u32 v238, v253, s29
	v_lshl_add_u32 v238, v140, 4, v238
	s_movk_i32 s29, 136
	v_mul_lo_u32 v239, v253, s29
	v_lshl_add_u32 v239, v140, 3, v239
	v_add_u32_e32 v240, 0x1100, v239
	v_mov_b32_e32 v225, v143
	s_mov_b32 s29, 0xaaab
	v_mul_u32_u24_e32 v226, 0xaaab, v225
	v_lshrrev_b32_e32 v226, 19, v226
	v_mul_u32_u24_e32 v227, 12, v226
	v_sub_u32_e32 v227, v225, v227
	s_movk_i32 s29, 192
	v_mul_lo_u32 v246, v226, s29
	v_lshl_add_u32 v246, v227, 4, v246
	s_movk_i32 s29, 208
	v_mul_lo_u32 v241, v226, s29
	v_lshl_add_u32 v241, v227, 4, v241
	v_add_u32_e32 v225, 256, v143
	s_mov_b32 s29, 0xaaab
	v_mul_u32_u24_e32 v226, 0xaaab, v225
	v_lshrrev_b32_e32 v226, 19, v226
	v_mul_u32_u24_e32 v227, 12, v226
	v_sub_u32_e32 v227, v225, v227
	s_movk_i32 s29, 192
	v_mul_lo_u32 v247, v226, s29
	v_lshl_add_u32 v247, v227, 4, v247
	s_movk_i32 s29, 208
	v_mul_lo_u32 v242, v226, s29
	v_lshl_add_u32 v242, v227, 4, v242
	v_add_u32_e32 v225, 512, v143
	s_mov_b32 s29, 0xaaab
	v_mul_u32_u24_e32 v226, 0xaaab, v225
	v_lshrrev_b32_e32 v226, 19, v226
	v_mul_u32_u24_e32 v227, 12, v226
	v_sub_u32_e32 v227, v225, v227
	s_movk_i32 s29, 192
	v_mul_lo_u32 v248, v226, s29
	v_lshl_add_u32 v248, v227, 4, v248
	s_movk_i32 s29, 208
	v_mul_lo_u32 v243, v226, s29
	v_lshl_add_u32 v243, v227, 4, v243
	v_lshrrev_b32_e32 v226, 3, v143
	v_and_b32_e32 v227, 7, v143
	s_movk_i32 s29, 8704
	v_mul_lo_u32 v249, v226, s29
	v_lshl_add_u32 v249, v227, 4, v249
	v_add_u32_e32 v250, 0x44000, v249
	s_movk_i32 s29, 136
	v_mul_lo_u32 v244, v226, s29
	v_lshl_add_u32 v244, v227, 4, v244
	v_add_u32_e32 v245, 0x1100, v244
	s_barrier
	global_load_dwordx4 v[112:115], v251, s[58:59] offset:0
	global_load_dwordx4 v[116:119], v251, s[58:59] offset:32
	global_load_dwordx4 v[120:123], v251, s[58:59] offset:64
	global_load_dwordx4 v[124:127], v251, s[58:59] offset:96
	global_load_dwordx4 v[128:131], v251, s[58:59] offset:128
	global_load_dwordx4 v[132:135], v251, s[58:59] offset:160
	s_mov_b32 s1, 0
	s_min_u32 s0, s1, 67
	s_mul_i32 s0, s0, 0x3000
	s_add_u32 s64, s60, s0
	s_addc_u32 s65, s61, 0
	s_min_u32 s0, s1, 67
	s_lshl_b32 s0, s0, 7
	s_add_u32 s66, s62, s0
	s_addc_u32 s67, s63, 0
	global_load_dwordx4 v[176:179], v246, s[64:65]
	global_load_dwordx4 v[180:183], v247, s[64:65]
	global_load_dwordx4 v[184:187], v248, s[64:65]
	global_load_dwordx4 v[212:215], v249, s[66:67]
	global_load_dwordx4 v[216:219], v250, s[66:67]
	s_waitcnt vmcnt(0)
	ds_write_b128 v241, v[176:179] offset:0
	ds_write_b128 v242, v[180:183] offset:0
	ds_write_b128 v243, v[184:187] offset:0
	ds_write_b64 v244, v[212:213] offset:26624
	ds_write_b64 v244, v[214:215] offset:26632
	ds_write_b64 v245, v[216:217] offset:26624
	ds_write_b64 v245, v[218:219] offset:26632
	s_mov_b32 s1, 1
	s_min_u32 s0, s1, 67
	s_mul_i32 s0, s0, 0x3000
	s_add_u32 s64, s60, s0
	s_addc_u32 s65, s61, 0
	s_min_u32 s0, s1, 67
	s_lshl_b32 s0, s0, 7
	s_add_u32 s66, s62, s0
	s_addc_u32 s67, s63, 0
	global_load_dwordx4 v[176:179], v246, s[64:65]
	global_load_dwordx4 v[180:183], v247, s[64:65]
	global_load_dwordx4 v[184:187], v248, s[64:65]
	s_waitcnt vmcnt(0)
	ds_write_b128 v241, v[176:179] offset:13312
	ds_write_b128 v242, v[180:183] offset:13312
	ds_write_b128 v243, v[184:187] offset:13312
	s_mov_b32 s1, 2
	s_mov_b32 s10, 1
	s_min_u32 s0, s1, 67
	s_mul_i32 s0, s0, 0x3000
	s_add_u32 s64, s60, s0
	s_addc_u32 s65, s61, 0
	s_min_u32 s0, s10, 67
	s_lshl_b32 s0, s0, 7
	s_add_u32 s66, s62, s0
	s_addc_u32 s67, s63, 0
	global_load_dwordx4 v[176:179], v246, s[64:65]
	global_load_dwordx4 v[180:183], v247, s[64:65]
	global_load_dwordx4 v[184:187], v248, s[64:65]
	global_load_dwordx4 v[212:215], v249, s[66:67]
	global_load_dwordx4 v[216:219], v250, s[66:67]
	v_mov_b32_e32 v0, 0
	v_mov_b32_e32 v1, 0
	v_mov_b32_e32 v2, 0
	v_mov_b32_e32 v3, 0
	v_mov_b32_e32 v4, 0
	v_mov_b32_e32 v5, 0
	v_mov_b32_e32 v6, 0
	v_mov_b32_e32 v7, 0
	v_mov_b32_e32 v8, 0
	v_mov_b32_e32 v9, 0
	v_mov_b32_e32 v10, 0
	v_mov_b32_e32 v11, 0
	v_mov_b32_e32 v12, 0
	v_mov_b32_e32 v13, 0
	v_mov_b32_e32 v14, 0
	v_mov_b32_e32 v15, 0
	v_mov_b32_e32 v16, 0
	v_mov_b32_e32 v17, 0
	v_mov_b32_e32 v18, 0
	v_mov_b32_e32 v19, 0
	v_mov_b32_e32 v20, 0
	v_mov_b32_e32 v21, 0
	v_mov_b32_e32 v22, 0
	v_mov_b32_e32 v23, 0
	v_mov_b32_e32 v24, 0
	v_mov_b32_e32 v25, 0
	v_mov_b32_e32 v26, 0
	v_mov_b32_e32 v27, 0
	v_mov_b32_e32 v28, 0
	v_mov_b32_e32 v29, 0
	v_mov_b32_e32 v30, 0
	v_mov_b32_e32 v31, 0
	v_mov_b32_e32 v221, 0
	s_waitcnt lgkmcnt(0)
	s_barrier
; template <int DQK>
; DI void attn_item(const bf16_t* __restrict__ Q, const bf16_t* __restrict__ Kp, const bf16_t* __restrict__ Vt, int q0, int nkeys,
;                   bf16_t* __restrict__ mix, int colbase, int b, char* smem) {
;     ...
;   const int nt = nkeys >> 6;
;   A_LOAD(p, 0)
;   A_LOAD(q, 64)
;   A_WRITE(p, 0)
;   __syncthreads();
;   if (nt > 2) A_LOAD(p, 128)
;   for (int kt = 0; kt < nt; kt += 2) {
;     A_TILE(0)
;     A_WRITE(q, 1)
;     __syncthreads();
;     if (kt + 3 < nt) A_LOAD(q, (kt + 3) << 6)
	ds_read_b128 v[144:147], v238 offset:0
	ds_read_b128 v[148:151], v238 offset:6656
	ds_read_b128 v[152:155], v238 offset:32
	ds_read_b128 v[156:159], v238 offset:6688
	s_waitcnt lgkmcnt(3)
	v_mfma_f32_32x32x16_bf16 v[32:47], v[144:147], v[112:115], 0
	ds_read_b128 v[144:147], v238 offset:64
	s_waitcnt lgkmcnt(3)
	v_mfma_f32_32x32x16_bf16 v[48:63], v[148:151], v[112:115], 0
	ds_read_b128 v[148:151], v238 offset:6720
	s_waitcnt lgkmcnt(3)
	v_mfma_f32_32x32x16_bf16 v[32:47], v[152:155], v[116:119], v[32:47]
	ds_read_b128 v[152:155], v238 offset:96
	s_waitcnt lgkmcnt(3)
	v_mfma_f32_32x32x16_bf16 v[48:63], v[156:159], v[116:119], v[48:63]
	ds_read_b128 v[156:159], v238 offset:6752
	s_waitcnt lgkmcnt(3)
	v_mfma_f32_32x32x16_bf16 v[32:47], v[144:147], v[120:123], v[32:47]
	ds_read_b128 v[144:147], v238 offset:128
	s_waitcnt lgkmcnt(3)
	v_mfma_f32_32x32x16_bf16 v[48:63], v[148:151], v[120:123], v[48:63]
	ds_read_b128 v[148:151], v238 offset:6784
	s_waitcnt lgkmcnt(3)
	v_mfma_f32_32x32x16_bf16 v[32:47], v[152:155], v[124:127], v[32:47]
	ds_read_b128 v[152:155], v238 offset:160
	s_waitcnt lgkmcnt(3)
	v_mfma_f32_32x32x16_bf16 v[48:63], v[156:159], v[124:127], v[48:63]
	ds_read_b128 v[156:159], v238 offset:6816
	s_waitcnt lgkmcnt(3)
	v_mfma_f32_32x32x16_bf16 v[32:47], v[144:147], v[128:131], v[32:47]
	s_waitcnt lgkmcnt(2)
	v_mfma_f32_32x32x16_bf16 v[48:63], v[148:151], v[128:131], v[48:63]
	s_waitcnt lgkmcnt(1)
	v_mfma_f32_32x32x16_bf16 v[32:47], v[152:155], v[132:135], v[32:47]
	s_waitcnt lgkmcnt(0)
	v_mfma_f32_32x32x16_bf16 v[48:63], v[156:159], v[132:135], v[48:63]
	s_waitcnt lgkmcnt(0)
	s_barrier
	s_nop 7
	s_nop 3
	v_max3_f32 v223, v32, v33, v34
	v_max3_f32 v224, v40, v41, v42
	v_max3_f32 v225, v48, v49, v50
	v_max3_f32 v226, v56, v57, v58
	v_max3_f32 v223, v223, v35, v36
	v_max3_f32 v224, v224, v43, v44
	v_max3_f32 v225, v225, v51, v52
	v_max3_f32 v226, v226, v59, v60
	v_max3_f32 v223, v223, v37, v38
	v_max3_f32 v224, v224, v45, v46
	v_max3_f32 v225, v225, v53, v54
	v_max3_f32 v226, v226, v61, v62
	v_max_f32_e32 v223, v223, v39
	v_max_f32_e32 v224, v224, v47
	v_max_f32_e32 v225, v225, v55
	v_max_f32_e32 v226, v226, v63
	v_max3_f32 v222, v223, v224, v225
	v_max_f32_e32 v222, v222, v226
	v_mov_b32_e32 v227, v222
	s_nop 1
	v_permlane32_swap_b32_e32 v222, v227
	v_max_f32_e32 v222, v222, v227
	v_sub_f32_e32 v32, v32, v222
	v_sub_f32_e32 v33, v33, v222
	v_sub_f32_e32 v34, v34, v222
	v_sub_f32_e32 v35, v35, v222
	v_sub_f32_e32 v36, v36, v222
	v_sub_f32_e32 v37, v37, v222
	v_sub_f32_e32 v38, v38, v222
	v_sub_f32_e32 v39, v39, v222
	v_sub_f32_e32 v40, v40, v222
	v_sub_f32_e32 v41, v41, v222
	v_sub_f32_e32 v42, v42, v222
	v_sub_f32_e32 v43, v43, v222
	v_sub_f32_e32 v44, v44, v222
	v_sub_f32_e32 v45, v45, v222
	v_sub_f32_e32 v46, v46, v222
	v_sub_f32_e32 v47, v47, v222
	v_sub_f32_e32 v48, v48, v222
	v_sub_f32_e32 v49, v49, v222
	v_sub_f32_e32 v50, v50, v222
	v_sub_f32_e32 v51, v51, v222
	v_sub_f32_e32 v52, v52, v222
	v_sub_f32_e32 v53, v53, v222
	v_sub_f32_e32 v54, v54, v222
	v_sub_f32_e32 v55, v55, v222
	v_sub_f32_e32 v56, v56, v222
	v_sub_f32_e32 v57, v57, v222
	v_sub_f32_e32 v58, v58, v222
	v_sub_f32_e32 v59, v59, v222
	v_sub_f32_e32 v60, v60, v222
	v_sub_f32_e32 v61, v61, v222
	v_sub_f32_e32 v62, v62, v222
	v_sub_f32_e32 v63, v63, v222
	v_sub_f32_e32 v160, 0, v222
	v_sub_f32_e32 v161, 0, v222
	v_sub_f32_e32 v162, 0, v222
	v_sub_f32_e32 v163, 0, v222
	v_sub_f32_e32 v164, 0, v222
	v_sub_f32_e32 v165, 0, v222
	v_sub_f32_e32 v166, 0, v222
	v_sub_f32_e32 v167, 0, v222
	v_sub_f32_e32 v168, 0, v222
	v_sub_f32_e32 v169, 0, v222
	v_sub_f32_e32 v170, 0, v222
	v_sub_f32_e32 v171, 0, v222
	v_sub_f32_e32 v172, 0, v222
	v_sub_f32_e32 v173, 0, v222
	v_sub_f32_e32 v174, 0, v222
	v_sub_f32_e32 v175, 0, v222
	s_mov_b32 s69, 0
	s_mov_b32 s68, 0
.Lat_loop_m:
	s_waitcnt vmcnt(0)
	ds_write_b128 v241, v[176:179] offset:0
	ds_write_b128 v242, v[180:183] offset:0
	ds_write_b128 v243, v[184:187] offset:0
	ds_write_b64 v244, v[212:213] offset:35328
	ds_write_b64 v244, v[214:215] offset:35336
	ds_write_b64 v245, v[216:217] offset:35328
	ds_write_b64 v245, v[218:219] offset:35336
	s_add_u32 s1, s68, 3
	s_add_u32 s10, s68, 2
	s_min_u32 s0, s1, 67
	s_mul_i32 s0, s0, 0x3000
	s_add_u32 s64, s60, s0
	s_addc_u32 s65, s61, 0
	s_min_u32 s0, s10, 67
	s_lshl_b32 s0, s0, 7
	s_add_u32 s66, s62, s0
	s_addc_u32 s67, s63, 0
	global_load_dwordx4 v[176:179], v246, s[64:65]
	global_load_dwordx4 v[180:183], v247, s[64:65]
	global_load_dwordx4 v[184:187], v248, s[64:65]
	global_load_dwordx4 v[212:215], v249, s[66:67]
	global_load_dwordx4 v[216:219], v250, s[66:67]
	s_cmp_eq_u32 s69, 0
	s_cbranch_scc1 .Lat_nopend_8
	v_sub_f32_e32 v32, v32, v220
	v_sub_f32_e32 v33, v33, v220
	v_sub_f32_e32 v34, v34, v220
	v_sub_f32_e32 v35, v35, v220
	v_sub_f32_e32 v36, v36, v220
	v_sub_f32_e32 v37, v37, v220
	v_sub_f32_e32 v38, v38, v220
	v_sub_f32_e32 v39, v39, v220
	v_sub_f32_e32 v40, v40, v220
	v_sub_f32_e32 v41, v41, v220
	v_sub_f32_e32 v42, v42, v220
	v_sub_f32_e32 v43, v43, v220
	v_sub_f32_e32 v44, v44, v220
	v_sub_f32_e32 v45, v45, v220
	v_sub_f32_e32 v46, v46, v220
	v_sub_f32_e32 v47, v47, v220
	v_sub_f32_e32 v48, v48, v220
	v_sub_f32_e32 v49, v49, v220
	v_sub_f32_e32 v50, v50, v220
	v_sub_f32_e32 v51, v51, v220
	v_sub_f32_e32 v52, v52, v220
	v_sub_f32_e32 v53, v53, v220
	v_sub_f32_e32 v54, v54, v220
	v_sub_f32_e32 v55, v55, v220
	v_sub_f32_e32 v56, v56, v220
	v_sub_f32_e32 v57, v57, v220
	v_sub_f32_e32 v58, v58, v220
	v_sub_f32_e32 v59, v59, v220
	v_sub_f32_e32 v60, v60, v220
	v_sub_f32_e32 v61, v61, v220
	v_sub_f32_e32 v62, v62, v220
	v_sub_f32_e32 v63, v63, v220
	s_mov_b32 s69, 0
.Lat_nopend_8:
	ds_read_b128 v[144:147], v238 offset:13312
	ds_read_b128 v[148:151], v238 offset:19968
	ds_read_b128 v[152:155], v238 offset:13344
	ds_read_b128 v[156:159], v238 offset:20000
	v_max3_f32 v223, v32, v33, v34
	v_max3_f32 v224, v40, v41, v42
	v_max3_f32 v225, v48, v49, v50
	v_max3_f32 v226, v56, v57, v58
	s_waitcnt lgkmcnt(3)
	v_mfma_f32_32x32x16_bf16 v[64:79], v[144:147], v[112:115], v[160:175]
	ds_read_b128 v[144:147], v238 offset:13376
	v_max3_f32 v223, v223, v35, v36
	v_max3_f32 v224, v224, v43, v44
	v_max3_f32 v225, v225, v51, v52
	v_max3_f32 v226, v226, v59, v60
	s_waitcnt lgkmcnt(3)
	v_mfma_f32_32x32x16_bf16 v[80:95], v[148:151], v[112:115], v[160:175]
	ds_read_b128 v[148:151], v238 offset:20032
	v_max3_f32 v223, v223, v37, v38
	v_max3_f32 v224, v224, v45, v46
	v_max3_f32 v225, v225, v53, v54
	v_max3_f32 v226, v226, v61, v62
	s_waitcnt lgkmcnt(3)
	v_mfma_f32_32x32x16_bf16 v[64:79], v[152:155], v[116:119], v[64:79]
	ds_read_b128 v[152:155], v238 offset:13408
	v_max_f32_e32 v223, v223, v39
	v_max_f32_e32 v224, v224, v47
	v_max_f32_e32 v225, v225, v55
	v_max_f32_e32 v226, v226, v63
	s_waitcnt lgkmcnt(3)
	v_mfma_f32_32x32x16_bf16 v[80:95], v[156:159], v[116:119], v[80:95]
	ds_read_b128 v[156:159], v238 offset:20064
	v_max3_f32 v222, v223, v224, v225
	v_max_f32_e32 v222, v222, v226
	v_mov_b32_e32 v227, v222
	v_mov_b32_e32 v228, 0x41000000
	s_waitcnt lgkmcnt(3)
	v_mfma_f32_32x32x16_bf16 v[64:79], v[144:147], v[120:123], v[64:79]
	ds_read_b128 v[144:147], v238 offset:13440
	s_nop 0
	v_permlane32_swap_b32_e32 v222, v227
	v_max_f32_e32 v222, v222, v227
	v_cmp_gt_f32_e32 vcc, v222, v228
	s_cbranch_vccz .Lat_nors_9
	v_max_f32_e32 v220, 0, v222
	v_sub_f32_e32 v230, 0, v220
	v_exp_f32_e32 v230, v230
	v_sub_f32_e32 v32, v32, v220
	v_sub_f32_e32 v33, v33, v220
	v_sub_f32_e32 v34, v34, v220
	v_sub_f32_e32 v35, v35, v220
	v_sub_f32_e32 v36, v36, v220
	v_sub_f32_e32 v37, v37, v220
	v_sub_f32_e32 v38, v38, v220
	v_sub_f32_e32 v39, v39, v220
	v_sub_f32_e32 v40, v40, v220
	v_sub_f32_e32 v41, v41, v220
	v_sub_f32_e32 v42, v42, v220
	v_sub_f32_e32 v43, v43, v220
	v_sub_f32_e32 v44, v44, v220
	v_sub_f32_e32 v45, v45, v220
	v_sub_f32_e32 v46, v46, v220
	v_sub_f32_e32 v47, v47, v220
	v_sub_f32_e32 v48, v48, v220
	v_sub_f32_e32 v49, v49, v220
	v_sub_f32_e32 v50, v50, v220
	v_sub_f32_e32 v51, v51, v220
	v_sub_f32_e32 v52, v52, v220
	v_sub_f32_e32 v53, v53, v220
	v_sub_f32_e32 v54, v54, v220
	v_sub_f32_e32 v55, v55, v220
	v_sub_f32_e32 v56, v56, v220
	v_sub_f32_e32 v57, v57, v220
	v_sub_f32_e32 v58, v58, v220
	v_sub_f32_e32 v59, v59, v220
	v_sub_f32_e32 v60, v60, v220
	v_sub_f32_e32 v61, v61, v220
	v_sub_f32_e32 v62, v62, v220
	v_sub_f32_e32 v63, v63, v220
	v_sub_f32_e32 v160, v160, v220
	v_sub_f32_e32 v161, v161, v220
	v_sub_f32_e32 v162, v162, v220
	v_sub_f32_e32 v163, v163, v220
	v_sub_f32_e32 v164, v164, v220
	v_sub_f32_e32 v165, v165, v220
	v_sub_f32_e32 v166, v166, v220
	v_sub_f32_e32 v167, v167, v220
	v_sub_f32_e32 v168, v168, v220
	v_sub_f32_e32 v169, v169, v220
	v_sub_f32_e32 v170, v170, v220
	v_sub_f32_e32 v171, v171, v220
	v_sub_f32_e32 v172, v172, v220
	v_sub_f32_e32 v173, v173, v220
	v_sub_f32_e32 v174, v174, v220
	v_sub_f32_e32 v175, v175, v220
	v_mul_f32_e32 v221, v221, v230
	v_mul_f32_e32 v0, v0, v230
	v_mul_f32_e32 v1, v1, v230
	v_mul_f32_e32 v2, v2, v230
	v_mul_f32_e32 v3, v3, v230
	v_mul_f32_e32 v4, v4, v230
	v_mul_f32_e32 v5, v5, v230
	v_mul_f32_e32 v6, v6, v230
	v_mul_f32_e32 v7, v7, v230
	v_mul_f32_e32 v8, v8, v230
	v_mul_f32_e32 v9, v9, v230
	v_mul_f32_e32 v10, v10, v230
	v_mul_f32_e32 v11, v11, v230
	v_mul_f32_e32 v12, v12, v230
	v_mul_f32_e32 v13, v13, v230
	v_mul_f32_e32 v14, v14, v230
	v_mul_f32_e32 v15, v15, v230
	v_mul_f32_e32 v16, v16, v230
	v_mul_f32_e32 v17, v17, v230
	v_mul_f32_e32 v18, v18, v230
	v_mul_f32_e32 v19, v19, v230
	v_mul_f32_e32 v20, v20, v230
	v_mul_f32_e32 v21, v21, v230
	v_mul_f32_e32 v22, v22, v230
	v_mul_f32_e32 v23, v23, v230
	v_mul_f32_e32 v24, v24, v230
	v_mul_f32_e32 v25, v25, v230
	v_mul_f32_e32 v26, v26, v230
	v_mul_f32_e32 v27, v27, v230
	v_mul_f32_e32 v28, v28, v230
	v_mul_f32_e32 v29, v29, v230
	v_mul_f32_e32 v30, v30, v230
	v_mul_f32_e32 v31, v31, v230
	s_mov_b32 s69, 1
.Lat_nors_9:
	s_waitcnt lgkmcnt(3)
	v_mfma_f32_32x32x16_bf16 v[80:95], v[148:151], v[120:123], v[80:95]
	ds_read_b128 v[148:151], v238 offset:20096
	v_exp_f32_e32 v32, v32
	v_exp_f32_e32 v33, v33
	v_exp_f32_e32 v34, v34
	v_exp_f32_e32 v35, v35
	s_waitcnt lgkmcnt(3)
	v_mfma_f32_32x32x16_bf16 v[64:79], v[152:155], v[124:127], v[64:79]
	ds_read_b128 v[152:155], v238 offset:13472
	v_exp_f32_e32 v36, v36
	v_exp_f32_e32 v37, v37
	v_exp_f32_e32 v38, v38
	v_exp_f32_e32 v39, v39
	s_waitcnt lgkmcnt(3)
	v_mfma_f32_32x32x16_bf16 v[80:95], v[156:159], v[124:127], v[80:95]
	ds_read_b128 v[156:159], v238 offset:20128
	v_exp_f32_e32 v40, v40
	v_exp_f32_e32 v41, v41
	v_exp_f32_e32 v42, v42
	v_exp_f32_e32 v43, v43
	s_waitcnt lgkmcnt(3)
	v_mfma_f32_32x32x16_bf16 v[64:79], v[144:147], v[128:131], v[64:79]
	v_exp_f32_e32 v44, v44
	v_exp_f32_e32 v45, v45
	v_exp_f32_e32 v46, v46
	v_exp_f32_e32 v47, v47
	s_waitcnt lgkmcnt(2)
	v_mfma_f32_32x32x16_bf16 v[80:95], v[148:151], v[128:131], v[80:95]
	v_exp_f32_e32 v48, v48
	v_exp_f32_e32 v49, v49
	v_exp_f32_e32 v50, v50
	v_exp_f32_e32 v51, v51
	s_waitcnt lgkmcnt(1)
	v_mfma_f32_32x32x16_bf16 v[64:79], v[152:155], v[132:135], v[64:79]
	v_exp_f32_e32 v52, v52
	v_exp_f32_e32 v53, v53
	v_exp_f32_e32 v54, v54
	v_exp_f32_e32 v55, v55
	s_waitcnt lgkmcnt(0)
; template <int DQK>
; DI void attn_item(const bf16_t* __restrict__ Q, const bf16_t* __restrict__ Kp, const bf16_t* __restrict__ Vt, int q0, int nkeys,
;                   bf16_t* __restrict__ mix, int colbase, int b, char* smem) {
;     ...
;   const int nt = nkeys >> 6;
;   A_LOAD(p, 0)
;   A_LOAD(q, 64)
;   A_WRITE(p, 0)
;   __syncthreads();
;   if (nt > 2) A_LOAD(p, 128)
;   for (int kt = 0; kt < nt; kt += 2) {
;     A_TILE(0)
;     A_WRITE(q, 1)
;     __syncthreads();
;     if (kt + 3 < nt) A_LOAD(q, (kt + 3) << 6)
;     A_TILE(1)
;     if (kt + 2 < nt) A_WRITE(p, 0)
;     __syncthreads();
	v_mfma_f32_32x32x16_bf16 v[80:95], v[156:159], v[132:135], v[80:95]
	v_exp_f32_e32 v56, v56
	v_exp_f32_e32 v57, v57
	v_exp_f32_e32 v58, v58
	v_exp_f32_e32 v59, v59
	v_exp_f32_e32 v60, v60
	v_exp_f32_e32 v61, v61
	v_exp_f32_e32 v62, v62
	v_exp_f32_e32 v63, v63
	v_add_u32_e32 v223, 0x6800, v239
	v_add_u32_e32 v224, 0x6800, v240
	ds_read2_b64 v[144:147], v223 offset0:0 offset1:2
	ds_read2_b64 v[148:151], v224 offset0:0 offset1:2
	ds_read2_b64 v[152:155], v223 offset0:4 offset1:6
	ds_read2_b64 v[156:159], v224 offset0:4 offset1:6
	v_cvt_pk_bf16_f32 v96, v32, v33
	v_cvt_pk_bf16_f32 v97, v34, v35
	v_cvt_pk_bf16_f32 v98, v36, v37
	v_cvt_pk_bf16_f32 v99, v38, v39
	v_add_f32_e32 v231, v32, v36
	v_add_f32_e32 v232, v33, v37
	v_add_f32_e32 v233, v34, v38
	v_add_f32_e32 v237, v35, v39
	s_waitcnt lgkmcnt(3)
	v_mfma_f32_32x32x16_bf16 v[0:15], v[144:147], v[96:99], v[0:15]
	ds_read2_b64 v[144:147], v223 offset0:8 offset1:10
	s_waitcnt lgkmcnt(3)
	v_mfma_f32_32x32x16_bf16 v[16:31], v[148:151], v[96:99], v[16:31]
	ds_read2_b64 v[148:151], v224 offset0:8 offset1:10
	v_cvt_pk_bf16_f32 v100, v40, v41
	v_cvt_pk_bf16_f32 v101, v42, v43
	v_cvt_pk_bf16_f32 v102, v44, v45
	v_cvt_pk_bf16_f32 v103, v46, v47
	v_add_f32_e32 v231, v231, v40
	v_add_f32_e32 v232, v232, v41
	v_add_f32_e32 v233, v233, v42
	v_add_f32_e32 v237, v237, v43
	v_add_f32_e32 v231, v231, v44
	v_add_f32_e32 v232, v232, v45
	v_add_f32_e32 v233, v233, v46
	v_add_f32_e32 v237, v237, v47
	s_waitcnt lgkmcnt(3)
	v_mfma_f32_32x32x16_bf16 v[0:15], v[152:155], v[100:103], v[0:15]
	ds_read2_b64 v[152:155], v223 offset0:12 offset1:14
	s_waitcnt lgkmcnt(3)
	v_mfma_f32_32x32x16_bf16 v[16:31], v[156:159], v[100:103], v[16:31]
	ds_read2_b64 v[156:159], v224 offset0:12 offset1:14
	v_cvt_pk_bf16_f32 v104, v48, v49
	v_cvt_pk_bf16_f32 v105, v50, v51
	v_cvt_pk_bf16_f32 v106, v52, v53
	v_cvt_pk_bf16_f32 v107, v54, v55
	v_add_f32_e32 v231, v231, v48
	v_add_f32_e32 v232, v232, v49
	v_add_f32_e32 v233, v233, v50
	v_add_f32_e32 v237, v237, v51
	v_add_f32_e32 v231, v231, v52
	v_add_f32_e32 v232, v232, v53
	v_add_f32_e32 v233, v233, v54
	v_add_f32_e32 v237, v237, v55
	s_waitcnt lgkmcnt(3)
	v_mfma_f32_32x32x16_bf16 v[0:15], v[144:147], v[104:107], v[0:15]
	s_waitcnt lgkmcnt(2)
	v_mfma_f32_32x32x16_bf16 v[16:31], v[148:151], v[104:107], v[16:31]
	v_cvt_pk_bf16_f32 v108, v56, v57
	v_cvt_pk_bf16_f32 v109, v58, v59
	v_cvt_pk_bf16_f32 v110, v60, v61
	v_cvt_pk_bf16_f32 v111, v62, v63
	v_add_f32_e32 v231, v231, v56
	v_add_f32_e32 v232, v232, v57
	v_add_f32_e32 v233, v233, v58
	v_add_f32_e32 v237, v237, v59
	v_add_f32_e32 v231, v231, v60
	v_add_f32_e32 v232, v232, v61
	v_add_f32_e32 v233, v233, v62
	v_add_f32_e32 v237, v237, v63
	s_waitcnt lgkmcnt(1)
	v_mfma_f32_32x32x16_bf16 v[0:15], v[152:155], v[108:111], v[0:15]
	s_waitcnt lgkmcnt(0)
	v_mfma_f32_32x32x16_bf16 v[16:31], v[156:159], v[108:111], v[16:31]
	v_add_f32_e32 v231, v231, v232
	v_add_f32_e32 v233, v233, v237
	v_add_f32_e32 v231, v231, v233
	v_add_f32_e32 v221, v221, v231
	s_add_u32 s68, s68, 1
	s_waitcnt lgkmcnt(0)
	s_barrier
	s_waitcnt vmcnt(0)
	ds_write_b128 v241, v[176:179] offset:13312
	ds_write_b128 v242, v[180:183] offset:13312
	ds_write_b128 v243, v[184:187] offset:13312
	ds_write_b64 v244, v[212:213] offset:26624
	ds_write_b64 v244, v[214:215] offset:26632
	ds_write_b64 v245, v[216:217] offset:26624
	ds_write_b64 v245, v[218:219] offset:26632
	s_add_u32 s1, s68, 3
	s_add_u32 s10, s68, 2
	s_min_u32 s0, s1, 67
	s_mul_i32 s0, s0, 0x3000
	s_add_u32 s64, s60, s0
	s_addc_u32 s65, s61, 0
	s_min_u32 s0, s10, 67
	s_lshl_b32 s0, s0, 7
	s_add_u32 s66, s62, s0
	s_addc_u32 s67, s63, 0
	global_load_dwordx4 v[176:179], v246, s[64:65]
	global_load_dwordx4 v[180:183], v247, s[64:65]
	global_load_dwordx4 v[184:187], v248, s[64:65]
	global_load_dwordx4 v[212:215], v249, s[66:67]
	global_load_dwordx4 v[216:219], v250, s[66:67]
	s_cmp_eq_u32 s69, 0
	s_cbranch_scc1 .Lat_nopend_10
	v_sub_f32_e32 v64, v64, v220
	v_sub_f32_e32 v65, v65, v220
	v_sub_f32_e32 v66, v66, v220
	v_sub_f32_e32 v67, v67, v220
	v_sub_f32_e32 v68, v68, v220
	v_sub_f32_e32 v69, v69, v220
	v_sub_f32_e32 v70, v70, v220
	v_sub_f32_e32 v71, v71, v220
	v_sub_f32_e32 v72, v72, v220
	v_sub_f32_e32 v73, v73, v220
	v_sub_f32_e32 v74, v74, v220
	v_sub_f32_e32 v75, v75, v220
	v_sub_f32_e32 v76, v76, v220
	v_sub_f32_e32 v77, v77, v220
	v_sub_f32_e32 v78, v78, v220
	v_sub_f32_e32 v79, v79, v220
	v_sub_f32_e32 v80, v80, v220
	v_sub_f32_e32 v81, v81, v220
	v_sub_f32_e32 v82, v82, v220
	v_sub_f32_e32 v83, v83, v220
	v_sub_f32_e32 v84, v84, v220
	v_sub_f32_e32 v85, v85, v220
	v_sub_f32_e32 v86, v86, v220
	v_sub_f32_e32 v87, v87, v220
	v_sub_f32_e32 v88, v88, v220
	v_sub_f32_e32 v89, v89, v220
	v_sub_f32_e32 v90, v90, v220
	v_sub_f32_e32 v91, v91, v220
	v_sub_f32_e32 v92, v92, v220
	v_sub_f32_e32 v93, v93, v220
	v_sub_f32_e32 v94, v94, v220
	v_sub_f32_e32 v95, v95, v220
	s_mov_b32 s69, 0
.Lat_nopend_10:
	ds_read_b128 v[144:147], v238 offset:0
	ds_read_b128 v[148:151], v238 offset:6656
	ds_read_b128 v[152:155], v238 offset:32
	ds_read_b128 v[156:159], v238 offset:6688
	v_max3_f32 v223, v64, v65, v66
	v_max3_f32 v224, v72, v73, v74
	v_max3_f32 v225, v80, v81, v82
	v_max3_f32 v226, v88, v89, v90
	s_waitcnt lgkmcnt(3)
	v_mfma_f32_32x32x16_bf16 v[32:47], v[144:147], v[112:115], v[160:175]
	ds_read_b128 v[144:147], v238 offset:64
	v_max3_f32 v223, v223, v67, v68
	v_max3_f32 v224, v224, v75, v76
	v_max3_f32 v225, v225, v83, v84
	v_max3_f32 v226, v226, v91, v92
	s_waitcnt lgkmcnt(3)
	v_mfma_f32_32x32x16_bf16 v[48:63], v[148:151], v[112:115], v[160:175]
	ds_read_b128 v[148:151], v238 offset:6720
	v_max3_f32 v223, v223, v69, v70
	v_max3_f32 v224, v224, v77, v78
	v_max3_f32 v225, v225, v85, v86
	v_max3_f32 v226, v226, v93, v94
	s_waitcnt lgkmcnt(3)
	v_mfma_f32_32x32x16_bf16 v[32:47], v[152:155], v[116:119], v[32:47]
	ds_read_b128 v[152:155], v238 offset:96
	v_max_f32_e32 v223, v223, v71
	v_max_f32_e32 v224, v224, v79
	v_max_f32_e32 v225, v225, v87
	v_max_f32_e32 v226, v226, v95
	s_waitcnt lgkmcnt(3)
	v_mfma_f32_32x32x16_bf16 v[48:63], v[156:159], v[116:119], v[48:63]
	ds_read_b128 v[156:159], v238 offset:6752
	v_max3_f32 v222, v223, v224, v225
	v_max_f32_e32 v222, v222, v226
	v_mov_b32_e32 v227, v222
	v_mov_b32_e32 v228, 0x41000000
	s_waitcnt lgkmcnt(3)
	v_mfma_f32_32x32x16_bf16 v[32:47], v[144:147], v[120:123], v[32:47]
	ds_read_b128 v[144:147], v238 offset:128
	s_nop 0
	v_permlane32_swap_b32_e32 v222, v227
	v_max_f32_e32 v222, v222, v227
	v_cmp_gt_f32_e32 vcc, v222, v228
	s_cbranch_vccz .Lat_nors_11
	v_max_f32_e32 v220, 0, v222
	v_sub_f32_e32 v230, 0, v220
	v_exp_f32_e32 v230, v230
	v_sub_f32_e32 v64, v64, v220
	v_sub_f32_e32 v65, v65, v220
	v_sub_f32_e32 v66, v66, v220
	v_sub_f32_e32 v67, v67, v220
	v_sub_f32_e32 v68, v68, v220
	v_sub_f32_e32 v69, v69, v220
	v_sub_f32_e32 v70, v70, v220
	v_sub_f32_e32 v71, v71, v220
	v_sub_f32_e32 v72, v72, v220
	v_sub_f32_e32 v73, v73, v220
	v_sub_f32_e32 v74, v74, v220
	v_sub_f32_e32 v75, v75, v220
	v_sub_f32_e32 v76, v76, v220
	v_sub_f32_e32 v77, v77, v220
	v_sub_f32_e32 v78, v78, v220
	v_sub_f32_e32 v79, v79, v220
	v_sub_f32_e32 v80, v80, v220
	v_sub_f32_e32 v81, v81, v220
	v_sub_f32_e32 v82, v82, v220
	v_sub_f32_e32 v83, v83, v220
	v_sub_f32_e32 v84, v84, v220
	v_sub_f32_e32 v85, v85, v220
	v_sub_f32_e32 v86, v86, v220
	v_sub_f32_e32 v87, v87, v220
	v_sub_f32_e32 v88, v88, v220
	v_sub_f32_e32 v89, v89, v220
	v_sub_f32_e32 v90, v90, v220
	v_sub_f32_e32 v91, v91, v220
	v_sub_f32_e32 v92, v92, v220
	v_sub_f32_e32 v93, v93, v220
	v_sub_f32_e32 v94, v94, v220
	v_sub_f32_e32 v95, v95, v220
	v_sub_f32_e32 v160, v160, v220
	v_sub_f32_e32 v161, v161, v220
	v_sub_f32_e32 v162, v162, v220
	v_sub_f32_e32 v163, v163, v220
	v_sub_f32_e32 v164, v164, v220
	v_sub_f32_e32 v165, v165, v220
	v_sub_f32_e32 v166, v166, v220
	v_sub_f32_e32 v167, v167, v220
	v_sub_f32_e32 v168, v168, v220
	v_sub_f32_e32 v169, v169, v220
	v_sub_f32_e32 v170, v170, v220
	v_sub_f32_e32 v171, v171, v220
	v_sub_f32_e32 v172, v172, v220
	v_sub_f32_e32 v173, v173, v220
	v_sub_f32_e32 v174, v174, v220
	v_sub_f32_e32 v175, v175, v220
	v_mul_f32_e32 v221, v221, v230
	v_mul_f32_e32 v0, v0, v230
	v_mul_f32_e32 v1, v1, v230
	v_mul_f32_e32 v2, v2, v230
	v_mul_f32_e32 v3, v3, v230
	v_mul_f32_e32 v4, v4, v230
	v_mul_f32_e32 v5, v5, v230
	v_mul_f32_e32 v6, v6, v230
	v_mul_f32_e32 v7, v7, v230
	v_mul_f32_e32 v8, v8, v230
	v_mul_f32_e32 v9, v9, v230
	v_mul_f32_e32 v10, v10, v230
	v_mul_f32_e32 v11, v11, v230
	v_mul_f32_e32 v12, v12, v230
	v_mul_f32_e32 v13, v13, v230
	v_mul_f32_e32 v14, v14, v230
	v_mul_f32_e32 v15, v15, v230
	v_mul_f32_e32 v16, v16, v230
	v_mul_f32_e32 v17, v17, v230
	v_mul_f32_e32 v18, v18, v230
	v_mul_f32_e32 v19, v19, v230
	v_mul_f32_e32 v20, v20, v230
	v_mul_f32_e32 v21, v21, v230
	v_mul_f32_e32 v22, v22, v230
	v_mul_f32_e32 v23, v23, v230
	v_mul_f32_e32 v24, v24, v230
	v_mul_f32_e32 v25, v25, v230
	v_mul_f32_e32 v26, v26, v230
	v_mul_f32_e32 v27, v27, v230
	v_mul_f32_e32 v28, v28, v230
	v_mul_f32_e32 v29, v29, v230
	v_mul_f32_e32 v30, v30, v230
	v_mul_f32_e32 v31, v31, v230
	s_mov_b32 s69, 1
; DI unsigned pack2(float lo, float hi) { f32x2_t v = {lo, hi}; bf16x2_t r = __builtin_convertvector(v, bf16x2_t); return __builtin_bit_cast(unsigned, r); }
; DI float xhalf_sum(float x) { auto r = __builtin_amdgcn_permlane32_swap(__float_as_uint(x), __float_as_uint(x), false, false); return __uint_as_float(r[0]) + __uint_as_float(r[1]); }
; template <int DQK>
; DI void attn_item(const bf16_t* __restrict__ Q, const bf16_t* __restrict__ Kp, const bf16_t* __restrict__ Vt, int q0, int nkeys,
;                   bf16_t* __restrict__ mix, int colbase, int b, char* smem) {
;     ...
;   const int nt = nkeys >> 6;
;   A_LOAD(p, 0)
;   A_LOAD(q, 64)
;   A_WRITE(p, 0)
;   __syncthreads();
;   if (nt > 2) A_LOAD(p, 128)
;   for (int kt = 0; kt < nt; kt += 2) {
;     A_TILE(0)
;     A_WRITE(q, 1)
;     __syncthreads();
;     if (kt + 3 < nt) A_LOAD(q, (kt + 3) << 6)
;     A_TILE(1)
;     if (kt + 2 < nt) A_WRITE(p, 0)
;     __syncthreads();
;     if (kt + 4 < nt) A_LOAD(p, (kt + 4) << 6)
;   }
;     ...
;   l = xhalf_sum(l);
;   const float inv = 1.0f / l;
;   const int kp = q0 + wave * 32 + r;
;   bf16_t* orow = mix + (size_t)row_of(b, kp) * D + colbase;
; #pragma unroll
;   for (int g = 0; g < 4; ++g) {
;     uint2 w0, w1;
;     w0.x = pack2(o0[4 * g] * inv, o0[4 * g + 1] * inv); w0.y = pack2(o0[4 * g + 2] * inv, o0[4 * g + 3] * inv);
;     w1.x = pack2(o1[4 * g] * inv, o1[4 * g + 1] * inv); w1.y = pack2(o1[4 * g + 2] * inv, o1[4 * g + 3] * inv);
;     *(uint2*)(orow + 8 * g + 4 * h) = w0;
;     *(uint2*)(orow + 32 + 8 * g + 4 * h) = w1;
;   }
.Lat_nors_11:
	s_waitcnt lgkmcnt(3)
	v_mfma_f32_32x32x16_bf16 v[48:63], v[148:151], v[120:123], v[48:63]
	ds_read_b128 v[148:151], v238 offset:6784
	v_exp_f32_e32 v64, v64
	v_exp_f32_e32 v65, v65
	v_exp_f32_e32 v66, v66
	v_exp_f32_e32 v67, v67
	s_waitcnt lgkmcnt(3)
	v_mfma_f32_32x32x16_bf16 v[32:47], v[152:155], v[124:127], v[32:47]
	ds_read_b128 v[152:155], v238 offset:160
	v_exp_f32_e32 v68, v68
	v_exp_f32_e32 v69, v69
	v_exp_f32_e32 v70, v70
	v_exp_f32_e32 v71, v71
	s_waitcnt lgkmcnt(3)
	v_mfma_f32_32x32x16_bf16 v[48:63], v[156:159], v[124:127], v[48:63]
	ds_read_b128 v[156:159], v238 offset:6816
	v_exp_f32_e32 v72, v72
	v_exp_f32_e32 v73, v73
	v_exp_f32_e32 v74, v74
	v_exp_f32_e32 v75, v75
	s_waitcnt lgkmcnt(3)
	v_mfma_f32_32x32x16_bf16 v[32:47], v[144:147], v[128:131], v[32:47]
	v_exp_f32_e32 v76, v76
	v_exp_f32_e32 v77, v77
	v_exp_f32_e32 v78, v78
	v_exp_f32_e32 v79, v79
	s_waitcnt lgkmcnt(2)
	v_mfma_f32_32x32x16_bf16 v[48:63], v[148:151], v[128:131], v[48:63]
	v_exp_f32_e32 v80, v80
	v_exp_f32_e32 v81, v81
	v_exp_f32_e32 v82, v82
	v_exp_f32_e32 v83, v83
	s_waitcnt lgkmcnt(1)
	v_mfma_f32_32x32x16_bf16 v[32:47], v[152:155], v[132:135], v[32:47]
	v_exp_f32_e32 v84, v84
	v_exp_f32_e32 v85, v85
	v_exp_f32_e32 v86, v86
	v_exp_f32_e32 v87, v87
	s_waitcnt lgkmcnt(0)
	v_mfma_f32_32x32x16_bf16 v[48:63], v[156:159], v[132:135], v[48:63]
	v_exp_f32_e32 v88, v88
	v_exp_f32_e32 v89, v89
	v_exp_f32_e32 v90, v90
	v_exp_f32_e32 v91, v91
	v_exp_f32_e32 v92, v92
	v_exp_f32_e32 v93, v93
	v_exp_f32_e32 v94, v94
	v_exp_f32_e32 v95, v95
	v_add_u32_e32 v223, 0x8a00, v239
	v_add_u32_e32 v224, 0x8a00, v240
	ds_read2_b64 v[144:147], v223 offset0:0 offset1:2
	ds_read2_b64 v[148:151], v224 offset0:0 offset1:2
	ds_read2_b64 v[152:155], v223 offset0:4 offset1:6
	ds_read2_b64 v[156:159], v224 offset0:4 offset1:6
	v_cvt_pk_bf16_f32 v96, v64, v65
	v_cvt_pk_bf16_f32 v97, v66, v67
	v_cvt_pk_bf16_f32 v98, v68, v69
	v_cvt_pk_bf16_f32 v99, v70, v71
	v_add_f32_e32 v231, v64, v68
	v_add_f32_e32 v232, v65, v69
	v_add_f32_e32 v233, v66, v70
	v_add_f32_e32 v237, v67, v71
	s_waitcnt lgkmcnt(3)
	v_mfma_f32_32x32x16_bf16 v[0:15], v[144:147], v[96:99], v[0:15]
	ds_read2_b64 v[144:147], v223 offset0:8 offset1:10
	s_waitcnt lgkmcnt(3)
	v_mfma_f32_32x32x16_bf16 v[16:31], v[148:151], v[96:99], v[16:31]
	ds_read2_b64 v[148:151], v224 offset0:8 offset1:10
	v_cvt_pk_bf16_f32 v100, v72, v73
	v_cvt_pk_bf16_f32 v101, v74, v75
	v_cvt_pk_bf16_f32 v102, v76, v77
	v_cvt_pk_bf16_f32 v103, v78, v79
	v_add_f32_e32 v231, v231, v72
	v_add_f32_e32 v232, v232, v73
	v_add_f32_e32 v233, v233, v74
	v_add_f32_e32 v237, v237, v75
	v_add_f32_e32 v231, v231, v76
	v_add_f32_e32 v232, v232, v77
	v_add_f32_e32 v233, v233, v78
	v_add_f32_e32 v237, v237, v79
	s_waitcnt lgkmcnt(3)
	v_mfma_f32_32x32x16_bf16 v[0:15], v[152:155], v[100:103], v[0:15]
	ds_read2_b64 v[152:155], v223 offset0:12 offset1:14
	s_waitcnt lgkmcnt(3)
	v_mfma_f32_32x32x16_bf16 v[16:31], v[156:159], v[100:103], v[16:31]
	ds_read2_b64 v[156:159], v224 offset0:12 offset1:14
	v_cvt_pk_bf16_f32 v104, v80, v81
	v_cvt_pk_bf16_f32 v105, v82, v83
	v_cvt_pk_bf16_f32 v106, v84, v85
	v_cvt_pk_bf16_f32 v107, v86, v87
	v_add_f32_e32 v231, v231, v80
	v_add_f32_e32 v232, v232, v81
	v_add_f32_e32 v233, v233, v82
	v_add_f32_e32 v237, v237, v83
	v_add_f32_e32 v231, v231, v84
	v_add_f32_e32 v232, v232, v85
	v_add_f32_e32 v233, v233, v86
	v_add_f32_e32 v237, v237, v87
	s_waitcnt lgkmcnt(3)
	v_mfma_f32_32x32x16_bf16 v[0:15], v[144:147], v[104:107], v[0:15]
	s_waitcnt lgkmcnt(2)
	v_mfma_f32_32x32x16_bf16 v[16:31], v[148:151], v[104:107], v[16:31]
	v_cvt_pk_bf16_f32 v108, v88, v89
	v_cvt_pk_bf16_f32 v109, v90, v91
	v_cvt_pk_bf16_f32 v110, v92, v93
	v_cvt_pk_bf16_f32 v111, v94, v95
	v_add_f32_e32 v231, v231, v88
	v_add_f32_e32 v232, v232, v89
	v_add_f32_e32 v233, v233, v90
	v_add_f32_e32 v237, v237, v91
	v_add_f32_e32 v231, v231, v92
	v_add_f32_e32 v232, v232, v93
	v_add_f32_e32 v233, v233, v94
	v_add_f32_e32 v237, v237, v95
	s_waitcnt lgkmcnt(1)
	v_mfma_f32_32x32x16_bf16 v[0:15], v[152:155], v[108:111], v[0:15]
	s_waitcnt lgkmcnt(0)
	v_mfma_f32_32x32x16_bf16 v[16:31], v[156:159], v[108:111], v[16:31]
	v_add_f32_e32 v231, v231, v232
	v_add_f32_e32 v233, v233, v237
	v_add_f32_e32 v231, v231, v233
	v_add_f32_e32 v221, v221, v231
	s_add_u32 s68, s68, 1
	s_waitcnt lgkmcnt(0)
	s_barrier
	s_cmp_lt_u32 s68, 68
	s_cbranch_scc1 .Lat_loop_m
	s_nop 7
	v_mov_b32_e32 v223, v221
	s_nop 1
	v_permlane32_swap_b32_e32 v221, v223
	v_add_f32_e32 v221, v221, v223
	v_rcp_f32_e32 v224, v221
	s_nop 0
	v_mul_f32_e32 v96, v0, v224
	v_mul_f32_e32 v97, v1, v224
	v_mul_f32_e32 v98, v2, v224
	v_mul_f32_e32 v99, v3, v224
	v_cvt_pk_bf16_f32 v144, v96, v97
	v_cvt_pk_bf16_f32 v145, v98, v99
	global_store_dwordx2 v252, v[144:145], s[72:73] offset:0
	v_mul_f32_e32 v96, v16, v224
	v_mul_f32_e32 v97, v17, v224
	v_mul_f32_e32 v98, v18, v224
	v_mul_f32_e32 v99, v19, v224
	v_cvt_pk_bf16_f32 v146, v96, v97
	v_cvt_pk_bf16_f32 v147, v98, v99
	global_store_dwordx2 v252, v[146:147], s[72:73] offset:64
	v_mul_f32_e32 v96, v4, v224
	v_mul_f32_e32 v97, v5, v224
	v_mul_f32_e32 v98, v6, v224
	v_mul_f32_e32 v99, v7, v224
	v_cvt_pk_bf16_f32 v148, v96, v97
	v_cvt_pk_bf16_f32 v149, v98, v99
	global_store_dwordx2 v252, v[148:149], s[72:73] offset:16
	v_mul_f32_e32 v96, v20, v224
	v_mul_f32_e32 v97, v21, v224
	v_mul_f32_e32 v98, v22, v224
	v_mul_f32_e32 v99, v23, v224
	v_cvt_pk_bf16_f32 v150, v96, v97
	v_cvt_pk_bf16_f32 v151, v98, v99
	global_store_dwordx2 v252, v[150:151], s[72:73] offset:80
	v_mul_f32_e32 v96, v8, v224
	v_mul_f32_e32 v97, v9, v224
	v_mul_f32_e32 v98, v10, v224
	v_mul_f32_e32 v99, v11, v224
	v_cvt_pk_bf16_f32 v152, v96, v97
	v_cvt_pk_bf16_f32 v153, v98, v99
	global_store_dwordx2 v252, v[152:153], s[72:73] offset:32
	v_mul_f32_e32 v96, v24, v224
	v_mul_f32_e32 v97, v25, v224
	v_mul_f32_e32 v98, v26, v224
	v_mul_f32_e32 v99, v27, v224
	v_cvt_pk_bf16_f32 v154, v96, v97
	v_cvt_pk_bf16_f32 v155, v98, v99
	global_store_dwordx2 v252, v[154:155], s[72:73] offset:96
	v_mul_f32_e32 v96, v12, v224
	v_mul_f32_e32 v97, v13, v224
	v_mul_f32_e32 v98, v14, v224
	v_mul_f32_e32 v99, v15, v224
	v_cvt_pk_bf16_f32 v156, v96, v97
	v_cvt_pk_bf16_f32 v157, v98, v99
	global_store_dwordx2 v252, v[156:157], s[72:73] offset:48
	v_mul_f32_e32 v96, v28, v224
	v_mul_f32_e32 v97, v29, v224
	v_mul_f32_e32 v98, v30, v224
	v_mul_f32_e32 v99, v31, v224
	v_cvt_pk_bf16_f32 v158, v96, v97
	v_cvt_pk_bf16_f32 v159, v98, v99
	global_store_dwordx2 v252, v[158:159], s[72:73] offset:112
